# hg_out chunk loop: rotating-register prefetch of token rows 16 tokens ahead (de-serialised loads) on top of v61
# speedup vs baseline: 1.0205x; 1.0205x over previous
.LBB0_686:
	s_ashr_i32 s24, s69, 9
	s_and_b32 s70, s67, 0x3f80
	s_ashr_i32 s25, s24, 31
	s_or_b32 s71, s70, 0x7f
	s_lshl_b64 s[56:57], s[24:25], 14
	s_mul_hi_i32 s3, s24, 0x3800000
	s_mul_i32 s24, s24, 0x3800000
	s_add_u32 s24, s50, s24
	s_addc_u32 s3, s51, s3
	s_lshl_b32 s54, s55, 1
	s_add_u32 s24, s24, s54
	s_addc_u32 s25, s3, 0
	s_lshl_b32 s3, s69, 1
	s_or_b32 s28, s3, s59
	v_ashrrev_i32_e32 v76, 4, v0
	s_ashr_i32 s29, s28, 31
	v_lshlrev_b32_e32 v77, 2, v76
	s_lshl_b64 s[28:29], s[28:29], 14
	v_and_b32_e32 v3, 15, v0
	v_lshlrev_b32_e32 v1, 8, v76
	v_or_b32_e32 v78, 1, v77
	s_add_u32 s28, s60, s28
	v_or_b32_e32 v4, v1, v3
	v_lshlrev_b32_e32 v22, 6, v78
	v_or_b32_e32 v24, 0x80, v1
	v_or_b32_e32 v26, 0xc0, v1
	s_addc_u32 s29, s61, s29
	v_ashrrev_i32_e32 v5, 31, v4
	v_or_b32_e32 v8, v22, v3
	v_or_b32_e32 v12, v24, v3
	v_or_b32_e32 v16, v26, v3
	v_lshl_add_u64 v[6:7], v[4:5], 2, s[28:29]
	v_ashrrev_i32_e32 v9, 31, v8
	v_ashrrev_i32_e32 v13, 31, v12
	v_ashrrev_i32_e32 v17, 31, v16
	v_ashrrev_i32_e32 v5, 31, v1
	v_lshl_add_u64 v[10:11], v[8:9], 2, s[28:29]
	v_lshl_add_u64 v[14:15], v[12:13], 2, s[28:29]
	v_lshl_add_u64 v[18:19], v[16:17], 2, s[28:29]
	v_lshl_add_u64 v[20:21], v[4:5], 2, s[28:29]
	v_ashrrev_i32_e32 v9, 31, v22
	v_ashrrev_i32_e32 v13, 31, v24
	v_ashrrev_i32_e32 v17, 31, v26
	v_add_u32_e32 v36, 0x400, v1
	v_lshl_add_u64 v[22:23], v[8:9], 2, s[28:29]
	v_lshl_add_u64 v[24:25], v[12:13], 2, s[28:29]
	v_lshl_add_u64 v[26:27], v[16:17], 2, s[28:29]
	global_load_dword v4, v[6:7], off
	global_load_dword v5, v[10:11], off
	s_nop 0
	global_load_dword v6, v[14:15], off
	global_load_dword v7, v[18:19], off
	global_load_dword v8, v[20:21], off offset:64
	global_load_dword v9, v[22:23], off offset:64
	global_load_dword v12, v[20:21], off offset:128
	global_load_dword v16, v[20:21], off offset:192
	global_load_dword v10, v[24:25], off offset:64
	global_load_dword v11, v[26:27], off offset:64
	global_load_dword v13, v[22:23], off offset:128
	global_load_dword v14, v[24:25], off offset:128
	global_load_dword v15, v[26:27], off offset:128
	global_load_dword v19, v[26:27], off offset:192
	global_load_dword v18, v[24:25], off offset:192
	global_load_dword v17, v[22:23], off offset:192
	v_or_b32_e32 v20, v36, v3
	v_add_u32_e32 v38, 0x440, v1
	v_add_u32_e32 v40, 0x480, v1
	v_add_u32_e32 v42, 0x4c0, v1
	v_ashrrev_i32_e32 v21, 31, v20
	v_or_b32_e32 v24, v38, v3
	v_or_b32_e32 v28, v40, v3
	v_or_b32_e32 v32, v42, v3
	v_lshl_add_u64 v[22:23], v[20:21], 2, s[28:29]
	v_ashrrev_i32_e32 v25, 31, v24
	v_ashrrev_i32_e32 v29, 31, v28
	v_ashrrev_i32_e32 v33, 31, v32
	v_ashrrev_i32_e32 v21, 31, v36
	v_lshl_add_u64 v[26:27], v[24:25], 2, s[28:29]
	v_lshl_add_u64 v[30:31], v[28:29], 2, s[28:29]
	v_lshl_add_u64 v[34:35], v[32:33], 2, s[28:29]
	v_lshl_add_u64 v[36:37], v[20:21], 2, s[28:29]
	v_ashrrev_i32_e32 v25, 31, v38
	v_ashrrev_i32_e32 v29, 31, v40
	v_ashrrev_i32_e32 v33, 31, v42
	v_add_u32_e32 v52, 0x800, v1
	v_add_u32_e32 v56, 0x880, v1
	v_lshl_add_u64 v[38:39], v[24:25], 2, s[28:29]
	v_lshl_add_u64 v[40:41], v[28:29], 2, s[28:29]
	v_lshl_add_u64 v[42:43], v[32:33], 2, s[28:29]
	global_load_dword v20, v[22:23], off
	global_load_dword v21, v[26:27], off
	s_nop 0
	global_load_dword v22, v[30:31], off
	global_load_dword v23, v[34:35], off
	global_load_dword v24, v[36:37], off offset:64
	global_load_dword v25, v[38:39], off offset:64
	global_load_dword v28, v[36:37], off offset:128
	global_load_dword v32, v[36:37], off offset:192
	global_load_dword v26, v[40:41], off offset:64
	global_load_dword v27, v[42:43], off offset:64
	global_load_dword v29, v[38:39], off offset:128
	global_load_dword v30, v[40:41], off offset:128
	global_load_dword v31, v[42:43], off offset:128
	global_load_dword v35, v[42:43], off offset:192
	global_load_dword v34, v[40:41], off offset:192
	global_load_dword v33, v[38:39], off offset:192
	v_or_b32_e32 v36, v52, v3
	v_add_u32_e32 v54, 0x840, v1
	v_or_b32_e32 v44, v56, v3
	v_add_u32_e32 v58, 0x8c0, v1
	v_ashrrev_i32_e32 v37, 31, v36
	v_or_b32_e32 v40, v54, v3
	v_ashrrev_i32_e32 v45, 31, v44
	v_or_b32_e32 v48, v58, v3
	v_lshl_add_u64 v[38:39], v[36:37], 2, s[28:29]
	v_ashrrev_i32_e32 v41, 31, v40
	v_lshl_add_u64 v[46:47], v[44:45], 2, s[28:29]
	v_ashrrev_i32_e32 v49, 31, v48
	v_ashrrev_i32_e32 v37, 31, v52
	v_ashrrev_i32_e32 v45, 31, v56
	v_lshl_add_u64 v[42:43], v[40:41], 2, s[28:29]
	v_lshl_add_u64 v[50:51], v[48:49], 2, s[28:29]
	v_lshl_add_u64 v[52:53], v[36:37], 2, s[28:29]
	v_ashrrev_i32_e32 v41, 31, v54
	v_lshl_add_u64 v[56:57], v[44:45], 2, s[28:29]
	v_ashrrev_i32_e32 v49, 31, v58
	v_add_u32_e32 v68, 0xc00, v1
	v_add_u32_e32 v70, 0xc40, v1
	v_add_u32_e32 v72, 0xc80, v1
	v_add_u32_e32 v1, 0xcc0, v1
	v_lshl_add_u64 v[54:55], v[40:41], 2, s[28:29]
	v_lshl_add_u64 v[58:59], v[48:49], 2, s[28:29]
	global_load_dword v36, v[38:39], off
	global_load_dword v37, v[42:43], off
	s_nop 0
	global_load_dword v38, v[46:47], off
	global_load_dword v39, v[50:51], off
	global_load_dword v40, v[52:53], off offset:64
	global_load_dword v41, v[54:55], off offset:64
	global_load_dword v44, v[52:53], off offset:128
	global_load_dword v48, v[52:53], off offset:192
	global_load_dword v42, v[56:57], off offset:64
	global_load_dword v43, v[58:59], off offset:64
	global_load_dword v45, v[54:55], off offset:128
	global_load_dword v46, v[56:57], off offset:128
	global_load_dword v47, v[58:59], off offset:128
	global_load_dword v51, v[58:59], off offset:192
	global_load_dword v50, v[56:57], off offset:192
	global_load_dword v49, v[54:55], off offset:192
	v_or_b32_e32 v52, v68, v3
	v_or_b32_e32 v56, v70, v3
	v_or_b32_e32 v60, v72, v3
	v_or_b32_e32 v64, v1, v3
	v_ashrrev_i32_e32 v53, 31, v52
	v_ashrrev_i32_e32 v57, 31, v56
	v_ashrrev_i32_e32 v61, 31, v60
	v_ashrrev_i32_e32 v65, 31, v64
	v_lshl_add_u64 v[54:55], v[52:53], 2, s[28:29]
	v_lshl_add_u64 v[58:59], v[56:57], 2, s[28:29]
	v_lshl_add_u64 v[62:63], v[60:61], 2, s[28:29]
	v_lshl_add_u64 v[66:67], v[64:65], 2, s[28:29]
	v_ashrrev_i32_e32 v53, 31, v68
	v_ashrrev_i32_e32 v57, 31, v70
	v_ashrrev_i32_e32 v61, 31, v72
	v_ashrrev_i32_e32 v65, 31, v1
	v_lshl_add_u64 v[68:69], v[52:53], 2, s[28:29]
	v_lshl_add_u64 v[70:71], v[56:57], 2, s[28:29]
	v_lshl_add_u64 v[72:73], v[60:61], 2, s[28:29]
	v_lshl_add_u64 v[74:75], v[64:65], 2, s[28:29]
	global_load_dword v52, v[54:55], off
	global_load_dword v53, v[58:59], off
	s_nop 0
	global_load_dword v54, v[62:63], off
	global_load_dword v55, v[66:67], off
	global_load_dword v56, v[68:69], off offset:64
	global_load_dword v57, v[70:71], off offset:64
	global_load_dword v60, v[68:69], off offset:128
	global_load_dword v64, v[68:69], off offset:192
	global_load_dword v58, v[72:73], off offset:64
	global_load_dword v59, v[74:75], off offset:64
	global_load_dword v61, v[70:71], off offset:128
	global_load_dword v62, v[72:73], off offset:128
	global_load_dword v63, v[74:75], off offset:128
	global_load_dword v67, v[74:75], off offset:192
	global_load_dword v66, v[72:73], off offset:192
	global_load_dword v65, v[70:71], off offset:192
	v_and_b32_e32 v68, -16, v0
	s_add_u32 s28, s63, s54
	v_add_u32_e32 v146, s58, v68
	v_lshlrev_b32_e32 v68, 4, v0
	s_addc_u32 s29, s62, 0
	v_and_b32_e32 v68, 0x70, v68
	v_mov_b32_e32 v69, v2
	v_add_u32_e32 v73, s58, v68
	v_lshl_add_u64 v[136:137], s[28:29], 0, v[68:69]
	v_ashrrev_i32_e32 v68, 3, v0
	v_mul_lo_u32 v69, v68, s78
	v_mul_lo_u32 v147, v68, s65
	v_add_u32_e32 v68, 64, v0
	v_ashrrev_i32_e32 v1, 31, v0
	s_movk_i32 s3, 0xffc4
	v_sub_u32_e32 v71, v3, v77
	v_lshlrev_b32_e32 v143, 6, v3
	v_ashrrev_i32_e32 v68, 3, v68
	v_lshl_add_u64 v[134:135], v[0:1], 1, s[24:25]
	v_lshl_add_u32 v140, v0, 1, s58
	v_lshl_add_u32 v141, v0, 6, s58
	v_mul_lo_u32 v1, v0, s3
	v_add_u32_e32 v145, s58, v143
	s_movk_i32 s3, 0xffc2
	v_cmp_gt_i32_e64 s[42:43], 2, v71
	v_cmp_gt_i32_e32 vcc, 3, v71
	v_mul_lo_u32 v75, v68, s78
	v_mul_lo_u32 v148, v68, s65
	v_add_u32_e32 v68, 0x80, v0
	v_add_u32_e32 v0, 0xc0, v0
	v_lshlrev_b32_e32 v142, 3, v76
	v_mad_i32_i24 v72, v3, s3, v145
	v_cmp_gt_i32_e64 s[40:41], 1, v71
	s_movk_i32 s3, 0x220
	v_ashrrev_i32_e32 v68, 3, v68
	v_ashrrev_i32_e32 v0, 3, v0
	s_and_b64 s[42:43], vcc, s[42:43]
	v_sub_f32_e32 v133, 1.0, v130
	v_add_u32_e32 v70, s58, v142
	v_mul_u32_u24_e32 v3, 0x88, v3
	v_cmp_gt_i32_e64 s[38:39], 0, v71
	v_mul_lo_u32 v71, v76, s3
	v_mul_lo_u32 v74, v78, s78
	v_mul_lo_u32 v76, v68, s78
	v_mul_lo_u32 v149, v68, s65
	v_mul_lo_u32 v68, v0, s78
	s_and_b64 s[40:41], s[42:43], s[40:41]
	s_mov_b32 s24, 0
	v_mul_lo_u32 v150, v0, s65
	v_mov_b32_e32 v138, v133
	v_mov_b32_e32 v139, v133
	v_mov_b32_e32 v131, v130
	v_add_u32_e32 v151, v141, v1
	v_add_u32_e32 v152, v70, v3
	v_add_u32_e32 v153, v72, v71
	v_add_u32_e32 v154, v72, v74
	v_add_u32_e32 v155, v73, v69
	v_add_u32_e32 v156, v73, v75
	v_add_u32_e32 v157, v73, v76
	v_add_u32_e32 v158, v73, v68
	s_and_b64 s[38:39], s[40:41], s[38:39]
	s_mul_i32 s98, s65, 0xe000
	s_ashr_i32 s99, s98, 31
	s_add_i32 s100, s70, s24
	s_and_b64 s[28:29], s[52:53], exec
	s_cselect_b32 s100, s100, s71
	s_mul_i32 s28, s100, 0xe00
	s_ashr_i32 s29, s28, 31
	v_lshl_add_u64 v[172:173], v[134:135], 0, s[28:29]
	v_lshl_add_u64 v[174:175], v[172:173], 0, s[26:27]
	global_load_ushort v180, v[174:175], off offset:1024
	global_load_ushort v196, v[172:173], off
	global_load_ushort v217, v[172:173], off offset:512
	s_add_i32 s100, s100, s65
	s_mul_i32 s28, s100, 0xe00
	s_ashr_i32 s29, s28, 31
	v_lshl_add_u64 v[172:173], v[134:135], 0, s[28:29]
	v_lshl_add_u64 v[174:175], v[172:173], 0, s[26:27]
	global_load_ushort v181, v[174:175], off offset:1024
	global_load_ushort v197, v[172:173], off
	global_load_ushort v218, v[172:173], off offset:512
	s_add_i32 s100, s100, s65
	s_mul_i32 s28, s100, 0xe00
	s_ashr_i32 s29, s28, 31
	v_lshl_add_u64 v[172:173], v[134:135], 0, s[28:29]
	v_lshl_add_u64 v[174:175], v[172:173], 0, s[26:27]
	global_load_ushort v182, v[174:175], off offset:1024
	global_load_ushort v198, v[172:173], off
	global_load_ushort v219, v[172:173], off offset:512
	s_add_i32 s100, s100, s65
	s_mul_i32 s28, s100, 0xe00
	s_ashr_i32 s29, s28, 31
	v_lshl_add_u64 v[172:173], v[134:135], 0, s[28:29]
	v_lshl_add_u64 v[174:175], v[172:173], 0, s[26:27]
	global_load_ushort v183, v[174:175], off offset:1024
	global_load_ushort v199, v[172:173], off
	global_load_ushort v220, v[172:173], off offset:512
	s_add_i32 s100, s100, s65
	s_mul_i32 s28, s100, 0xe00
	s_ashr_i32 s29, s28, 31
	v_lshl_add_u64 v[172:173], v[134:135], 0, s[28:29]
	v_lshl_add_u64 v[174:175], v[172:173], 0, s[26:27]
	global_load_ushort v184, v[174:175], off offset:1024
	global_load_ushort v200, v[172:173], off
	global_load_ushort v221, v[172:173], off offset:512
	s_add_i32 s100, s100, s65
	s_mul_i32 s28, s100, 0xe00
	s_ashr_i32 s29, s28, 31
	v_lshl_add_u64 v[172:173], v[134:135], 0, s[28:29]
	v_lshl_add_u64 v[174:175], v[172:173], 0, s[26:27]
	global_load_ushort v185, v[174:175], off offset:1024
	global_load_ushort v206, v[172:173], off
	global_load_ushort v222, v[172:173], off offset:512
	s_add_i32 s100, s100, s65
	s_mul_i32 s28, s100, 0xe00
	s_ashr_i32 s29, s28, 31
	v_lshl_add_u64 v[172:173], v[134:135], 0, s[28:29]
	v_lshl_add_u64 v[174:175], v[172:173], 0, s[26:27]
	global_load_ushort v186, v[174:175], off offset:1024
	global_load_ushort v207, v[172:173], off
	global_load_ushort v223, v[172:173], off offset:512
	s_add_i32 s100, s100, s65
	s_mul_i32 s28, s100, 0xe00
	s_ashr_i32 s29, s28, 31
	v_lshl_add_u64 v[172:173], v[134:135], 0, s[28:29]
	v_lshl_add_u64 v[174:175], v[172:173], 0, s[26:27]
	global_load_ushort v187, v[174:175], off offset:1024
	global_load_ushort v208, v[172:173], off
	global_load_ushort v224, v[172:173], off offset:512
	s_add_i32 s100, s100, s65
	s_mul_i32 s28, s100, 0xe00
	s_ashr_i32 s29, s28, 31
	v_lshl_add_u64 v[172:173], v[134:135], 0, s[28:29]
	v_lshl_add_u64 v[174:175], v[172:173], 0, s[26:27]
	global_load_ushort v188, v[174:175], off offset:1024
	global_load_ushort v209, v[172:173], off
	global_load_ushort v225, v[172:173], off offset:512
	s_add_i32 s100, s100, s65
	s_mul_i32 s28, s100, 0xe00
	s_ashr_i32 s29, s28, 31
	v_lshl_add_u64 v[172:173], v[134:135], 0, s[28:29]
	v_lshl_add_u64 v[174:175], v[172:173], 0, s[26:27]
	global_load_ushort v189, v[174:175], off offset:1024
	global_load_ushort v210, v[172:173], off
	global_load_ushort v245, v[172:173], off offset:512
	s_add_i32 s100, s100, s65
	s_mul_i32 s28, s100, 0xe00
	s_ashr_i32 s29, s28, 31
	v_lshl_add_u64 v[172:173], v[134:135], 0, s[28:29]
	v_lshl_add_u64 v[174:175], v[172:173], 0, s[26:27]
	global_load_ushort v190, v[174:175], off offset:1024
	global_load_ushort v211, v[172:173], off
	global_load_ushort v246, v[172:173], off offset:512
	s_add_i32 s100, s100, s65
	s_mul_i32 s28, s100, 0xe00
	s_ashr_i32 s29, s28, 31
	v_lshl_add_u64 v[172:173], v[134:135], 0, s[28:29]
	v_lshl_add_u64 v[174:175], v[172:173], 0, s[26:27]
	global_load_ushort v191, v[174:175], off offset:1024
	global_load_ushort v212, v[172:173], off
	global_load_ushort v248, v[172:173], off offset:512
	s_add_i32 s100, s100, s65
	s_mul_i32 s28, s100, 0xe00
	s_ashr_i32 s29, s28, 31
	v_lshl_add_u64 v[172:173], v[134:135], 0, s[28:29]
	v_lshl_add_u64 v[174:175], v[172:173], 0, s[26:27]
	global_load_ushort v192, v[174:175], off offset:1024
	global_load_ushort v213, v[172:173], off
	global_load_ushort v249, v[172:173], off offset:512
	s_add_i32 s100, s100, s65
	s_mul_i32 s28, s100, 0xe00
	s_ashr_i32 s29, s28, 31
	v_lshl_add_u64 v[172:173], v[134:135], 0, s[28:29]
	v_lshl_add_u64 v[174:175], v[172:173], 0, s[26:27]
	global_load_ushort v193, v[174:175], off offset:1024
	global_load_ushort v214, v[172:173], off
	global_load_ushort v250, v[172:173], off offset:512
	s_add_i32 s100, s100, s65
	s_mul_i32 s28, s100, 0xe00
	s_ashr_i32 s29, s28, 31
	v_lshl_add_u64 v[172:173], v[134:135], 0, s[28:29]
	v_lshl_add_u64 v[174:175], v[172:173], 0, s[26:27]
	global_load_ushort v194, v[174:175], off offset:1024
	global_load_ushort v215, v[172:173], off
	global_load_ushort v251, v[172:173], off offset:512
	s_add_i32 s100, s100, s65
	s_mul_i32 s28, s100, 0xe00
	s_ashr_i32 s29, s28, 31
	v_lshl_add_u64 v[172:173], v[134:135], 0, s[28:29]
	v_lshl_add_u64 v[174:175], v[172:173], 0, s[26:27]
	global_load_ushort v195, v[174:175], off offset:1024
	global_load_ushort v216, v[172:173], off
	global_load_ushort v252, v[172:173], off offset:512
	s_add_i32 s100, s100, s65
	s_waitcnt vmcnt(0)
.LBB0_687:
	s_cmpk_eq_i32 s24, 0x60
	s_cselect_b32 s100, 0, s98
	s_cselect_b32 s101, 0, s99
	s_add_i32 s3, s70, s24
	s_and_b64 s[28:29], s[52:53], exec
	s_cselect_b32 s3, s3, s71
	s_mul_i32 s28, s3, 0xe00
	s_ashr_i32 s29, s28, 31
	v_lshl_add_u64 v[68:69], v[134:135], 0, s[28:29]
	v_lshl_add_u64 v[0:1], v[68:69], 0, s[26:27]
	v_lshl_add_u64 v[172:173], v[0:1], 0, s[98:99]
	s_waitcnt vmcnt(51)
	v_mov_b32_e32 v0, v180
	global_load_ushort v180, v[172:173], off offset:1024
	s_add_i32 s25, s3, s65
	s_mul_i32 s28, s25, 0xe00
	s_ashr_i32 s29, s28, 31
	v_lshl_add_u64 v[74:75], v[134:135], 0, s[28:29]
	v_lshl_add_u64 v[76:77], v[74:75], 0, s[26:27]
	s_add_i32 s25, s25, s65
	s_mul_i32 s28, s25, 0xe00
	s_ashr_i32 s29, s28, 31
	s_add_i32 s25, s25, s65
	s_add_i32 s24, s24, 32
	s_sub_i32 s71, s71, 32
	s_nop 0
	v_lshlrev_b32_e32 v0, 16, v0
	v_max_f32_e32 v0, v0, v0
	v_max_f32_e32 v1, 0xc2700000, v0
	v_mul_f32_e32 v1, 0xbfb8aa3b, v1
	v_exp_f32_e32 v70, v1
	v_lshl_add_u64 v[174:175], v[68:69], 0, s[98:99]
	s_waitcnt vmcnt(51)
	v_mov_b32_e32 v0, v217
	global_load_ushort v217, v[174:175], off offset:512
	v_add_f32_e32 v1, 1.0, v70
	v_rcp_f32_e32 v72, v1
	v_lshl_add_u64 v[172:173], v[76:77], 0, s[98:99]
	s_waitcnt vmcnt(51)
	v_mov_b32_e32 v1, v181
	global_load_ushort v181, v[172:173], off offset:1024
	s_nop 0
	v_lshlrev_b32_e32 v1, 16, v1
	v_max_f32_e32 v1, v1, v1
	v_max_f32_e32 v1, 0xc2700000, v1
	v_mul_f32_e32 v1, 0xbfb8aa3b, v1
	v_exp_f32_e32 v71, v1
	s_nop 0
	v_add_f32_e32 v1, 1.0, v71
	v_rcp_f32_e32 v73, v1
	v_pk_mul_f32 v[70:71], v[138:139], v[70:71]
	v_pk_fma_f32 v[76:77], v[138:139], v[72:73], v[130:131]
	s_nop 0
	v_max_f32_e32 v1, 0xda24260, v76
	v_rcp_f32_e32 v78, v1
	v_lshl_add_u64 v[174:175], v[74:75], 0, s[98:99]
	s_waitcnt vmcnt(50)
	v_mov_b32_e32 v1, v197
	global_load_ushort v197, v[174:175], off
	v_lshl_add_u64 v[172:173], v[68:69], 0, s[98:99]
	s_nop 0
	v_mov_b32_e32 v3, v196
	global_load_ushort v196, v[172:173], off
	v_pk_mul_f32 v[70:71], v[70:71], v[72:73]
	v_lshl_add_u64 v[72:73], v[134:135], 0, s[28:29]
	v_lshl_add_u64 v[80:81], v[72:73], 0, s[26:27]
	v_mov_b32_e32 v132, v76
	v_mov_b32_e32 v82, v77
	s_mul_i32 s28, s25, 0xe00
	s_ashr_i32 s29, s28, 31
	s_add_i32 s25, s25, s65
	s_nop 0
	v_lshlrev_b32_e32 v69, 16, v1
	v_lshl_add_u64 v[174:175], v[80:81], 0, s[98:99]
	s_waitcnt vmcnt(51)
	v_mov_b32_e32 v1, v182
	global_load_ushort v182, v[174:175], off offset:1024
	s_nop 0
	v_lshlrev_b32_e32 v68, 16, v3
	s_nop 0
	v_lshlrev_b32_e32 v1, 16, v1
	v_max_f32_e32 v1, v1, v1
	v_max_f32_e32 v3, 0xc2700000, v1
	v_mul_f32_e32 v3, 0xbfb8aa3b, v3
	v_exp_f32_e32 v80, v3
	v_lshl_add_u64 v[172:173], v[72:73], 0, s[98:99]
	s_waitcnt vmcnt(50)
	v_mov_b32_e32 v1, v219
	global_load_ushort v219, v[172:173], off offset:512
	v_add_f32_e32 v3, 1.0, v80
	v_rcp_f32_e32 v83, v3
	s_nop 0
	v_pk_mul_f32 v[84:85], v[132:133], v[82:83]
	s_nop 0
	v_max_f32_e32 v3, 0xda24260, v84
	v_rcp_f32_e32 v79, v3
	v_mov_b32_e32 v77, v84
	v_pk_mul_f32 v[76:77], v[76:77], v[68:69]
	v_pk_mul_f32 v[70:71], v[70:71], v[78:79]
	s_nop 0
	v_cvt_pk_bf16_f32 v68, v70, v71
	v_cvt_pk_bf16_f32 v3, v76, v77
	v_lshl_add_u64 v[70:71], v[134:135], 0, s[28:29]
	ds_write_b16 v140, v3
	ds_write_b16_d16_hi v140, v3 offset:136
	ds_write_b16 v140, v68 offset:4352
	ds_write_b16_d16_hi v140, v68 offset:4488
	v_lshl_add_u64 v[76:77], v[70:71], 0, s[26:27]
	v_lshl_add_u64 v[174:175], v[76:77], 0, s[98:99]
	s_nop 0
	v_mov_b32_e32 v69, v183
	global_load_ushort v183, v[174:175], off offset:1024
	v_add_f32_e32 v3, v130, v85
	v_mul_f32_e32 v78, v84, v3
	v_max_f32_e32 v3, 0xda24260, v78
	v_rcp_f32_e32 v84, v3
	v_mov_b32_e32 v76, v83
	s_mul_i32 s28, s25, 0xe00
	s_ashr_i32 s29, s28, 31
	s_add_i32 s25, s25, s65
	s_nop 0
	v_lshlrev_b32_e32 v69, 16, v69
	v_max_f32_e32 v69, v69, v69
	v_max_f32_e32 v69, 0xc2700000, v69
	v_mul_f32_e32 v69, 0xbfb8aa3b, v69
	v_exp_f32_e32 v81, v69
	s_nop 0
	v_add_f32_e32 v69, 1.0, v81
	v_rcp_f32_e32 v77, v69
	v_pk_mul_f32 v[80:81], v[138:139], v[80:81]
	v_fma_f32 v69, v133, v77, v130
	v_mul_f32_e32 v79, v78, v69
	v_lshl_add_u64 v[172:173], v[70:71], 0, s[98:99]
	s_waitcnt vmcnt(50)
	v_mov_b32_e32 v3, v199
	global_load_ushort v199, v[172:173], off
	v_lshl_add_u64 v[174:175], v[72:73], 0, s[98:99]
	s_nop 0
	v_mov_b32_e32 v69, v198
	global_load_ushort v198, v[174:175], off
	v_pk_mul_f32 v[76:77], v[80:81], v[76:77]
	s_nop 0
	v_lshlrev_b32_e32 v73, 16, v3
	v_max_f32_e32 v3, 0xda24260, v79
	v_rcp_f32_e32 v85, v3
	s_nop 0
	v_lshlrev_b32_e32 v72, 16, v69
	v_pk_mul_f32 v[72:73], v[78:79], v[72:73]
	v_lshl_add_u64 v[172:173], v[70:71], 0, s[98:99]
	s_waitcnt vmcnt(51)
	v_mov_b32_e32 v3, v220
	global_load_ushort v220, v[172:173], off offset:512
	v_lshl_add_u64 v[174:175], v[74:75], 0, s[98:99]
	s_waitcnt vmcnt(51)
	v_mov_b32_e32 v80, v218
	global_load_ushort v218, v[174:175], off offset:512
	v_pk_mul_f32 v[76:77], v[76:77], v[84:85]
	v_cvt_pk_bf16_f32 v72, v72, v73
	v_lshl_add_u64 v[70:71], v[134:135], 0, s[28:29]
	v_cvt_pk_bf16_f32 v69, v76, v77
	ds_write_b16 v140, v72 offset:272
	ds_write_b16_d16_hi v140, v72 offset:408
	ds_write_b16 v140, v69 offset:4624
	ds_write_b16_d16_hi v140, v69 offset:4760
	v_lshl_add_u64 v[72:73], v[70:71], 0, s[26:27]
	v_lshl_add_u64 v[172:173], v[72:73], 0, s[98:99]
	s_waitcnt vmcnt(51)
	v_mov_b32_e32 v72, v184
	global_load_ushort v184, v[172:173], off offset:1024
	s_mul_i32 s28, s25, 0xe00
	v_lshl_add_u64 v[174:175], v[70:71], 0, s[98:99]
	s_waitcnt vmcnt(51)
	v_mov_b32_e32 v81, v221
	global_load_ushort v221, v[174:175], off offset:512
	s_ashr_i32 s29, s28, 31
	v_lshl_add_u64 v[76:77], v[134:135], 0, s[28:29]
	v_lshl_add_u64 v[82:83], v[76:77], 0, s[26:27]
	s_add_i32 s25, s25, s65
	s_mul_i32 s28, s25, 0xe00
	s_ashr_i32 s29, s28, 31
	s_add_i32 s25, s25, s65
	s_nop 0
	v_lshl_or_b32 v80, v80, 16, v0
	v_add_u32_e32 v0, 0x1000, v152
	s_nop 0
	v_lshlrev_b32_e32 v72, 16, v72
	v_max_f32_e32 v72, v72, v72
	v_max_f32_e32 v72, 0xc2700000, v72
	v_mul_f32_e32 v72, 0xbfb8aa3b, v72
	v_exp_f32_e32 v72, v72
	s_nop 0
	v_add_f32_e32 v73, 1.0, v72
	v_rcp_f32_e32 v74, v73
	v_lshl_add_u64 v[172:173], v[82:83], 0, s[98:99]
	s_waitcnt vmcnt(51)
	v_mov_b32_e32 v73, v185
	global_load_ushort v185, v[172:173], off offset:1024
	s_nop 0
	v_lshl_add_u64 v[174:175], v[70:71], 0, s[98:99]
	s_waitcnt vmcnt(51)
	v_mov_b32_e32 v70, v200
	global_load_ushort v200, v[174:175], off
	s_nop 0
	v_lshl_add_u64 v[172:173], v[76:77], 0, s[98:99]
	s_waitcnt vmcnt(51)
	v_mov_b32_e32 v71, v206
	global_load_ushort v206, v[172:173], off
	v_fma_f32 v78, v133, v74, v130
	v_mul_f32_e32 v78, v79, v78
	v_max_f32_e32 v79, 0xda24260, v78
	v_rcp_f32_e32 v82, v79
	s_nop 0
	v_lshlrev_b32_e32 v70, 16, v70
	v_lshlrev_b32_e32 v73, 16, v73
	v_max_f32_e32 v73, v73, v73
	v_max_f32_e32 v73, 0xc2700000, v73
	v_mul_f32_e32 v73, 0xbfb8aa3b, v73
	v_exp_f32_e32 v73, v73
	s_nop 0
	v_lshlrev_b32_e32 v71, 16, v71
	v_add_f32_e32 v75, 1.0, v73
	v_rcp_f32_e32 v75, v75
	s_nop 0
	v_fma_f32 v83, v133, v75, v130
	v_mul_f32_e32 v79, v78, v83
	v_pk_mul_f32 v[84:85], v[78:79], v[70:71]
	v_max_f32_e32 v70, 0xda24260, v79
	v_rcp_f32_e32 v83, v70
	v_pk_mul_f32 v[70:71], v[138:139], v[72:73]
	v_lshl_add_u64 v[72:73], v[134:135], 0, s[28:29]
	v_pk_mul_f32 v[70:71], v[70:71], v[74:75]
	v_lshl_add_u64 v[74:75], v[72:73], 0, s[26:27]
	v_pk_mul_f32 v[70:71], v[70:71], v[82:83]
	v_lshl_add_u64 v[174:175], v[76:77], 0, s[98:99]
	s_waitcnt vmcnt(45)
	v_mov_b32_e32 v82, v222
	global_load_ushort v222, v[174:175], off offset:512
	v_cvt_pk_bf16_f32 v70, v70, v71
	v_cvt_pk_bf16_f32 v71, v84, v85
	ds_write_b16 v140, v71 offset:544
	ds_write_b16_d16_hi v140, v71 offset:680
	ds_write_b16 v140, v70 offset:4896
	ds_write_b16_d16_hi v140, v70 offset:5032
	v_lshl_add_u64 v[172:173], v[74:75], 0, s[98:99]
	s_nop 0
	v_mov_b32_e32 v71, v186
	global_load_ushort v186, v[172:173], off offset:1024
	v_lshl_add_u64 v[174:175], v[72:73], 0, s[98:99]
	s_nop 0
	v_mov_b32_e32 v83, v223
	global_load_ushort v223, v[174:175], off offset:512
	s_mul_i32 s28, s25, 0xe00
	s_ashr_i32 s29, s28, 31
	v_lshl_add_u64 v[84:85], v[134:135], 0, s[28:29]
	v_lshl_add_u64 v[86:87], v[84:85], 0, s[26:27]
	v_lshl_add_u64 v[172:173], v[86:87], 0, s[98:99]
	s_nop 0
	v_mov_b32_e32 v75, v187
	global_load_ushort v187, v[172:173], off offset:1024
	s_add_i32 s25, s25, s65
	s_mul_i32 s28, s25, 0xe00
	s_ashr_i32 s29, s28, 31
	s_add_i32 s25, s25, s65
	s_nop 0
	v_lshl_or_b32 v82, v82, 16, v81
	v_lshl_or_b32 v81, v3, 16, v1
	v_add_u32_e32 v1, 0x1800, v152
	s_nop 0
	v_lshlrev_b32_e32 v71, 16, v71
	v_max_f32_e32 v71, v71, v71
	v_max_f32_e32 v71, 0xc2700000, v71
	v_mul_f32_e32 v71, 0xbfb8aa3b, v71
	v_exp_f32_e32 v74, v71
	s_nop 0
	v_lshlrev_b32_e32 v75, 16, v75
	v_max_f32_e32 v75, v75, v75
	v_add_f32_e32 v71, 1.0, v74
	v_rcp_f32_e32 v76, v71
	v_max_f32_e32 v75, 0xc2700000, v75
	v_mul_f32_e32 v75, 0xbfb8aa3b, v75
	v_exp_f32_e32 v75, v75
	v_fma_f32 v71, v133, v76, v130
	v_mul_f32_e32 v78, v79, v71
	v_max_f32_e32 v71, 0xda24260, v78
	v_rcp_f32_e32 v86, v71
	v_lshl_add_u64 v[174:175], v[72:73], 0, s[98:99]
	s_nop 0
	v_mov_b32_e32 v71, v207
	global_load_ushort v207, v[174:175], off
	s_nop 0
	v_lshl_add_u64 v[172:173], v[84:85], 0, s[98:99]
	s_nop 0
	v_mov_b32_e32 v72, v208
	global_load_ushort v208, v[172:173], off
	v_add_f32_e32 v77, 1.0, v75
	v_rcp_f32_e32 v77, v77
	v_pk_mul_f32 v[74:75], v[138:139], v[74:75]
	v_lshl_add_u64 v[174:175], v[84:85], 0, s[98:99]
	s_nop 0
	v_mov_b32_e32 v84, v224
	global_load_ushort v224, v[174:175], off offset:512
	v_fma_f32 v87, v133, v77, v130
	v_mul_f32_e32 v79, v78, v87
	v_pk_mul_f32 v[74:75], v[74:75], v[76:77]
	s_nop 0
	v_lshlrev_b32_e32 v73, 16, v72
	v_lshlrev_b32_e32 v72, 16, v71
	v_max_f32_e32 v71, 0xda24260, v79
	v_rcp_f32_e32 v87, v71
	v_pk_mul_f32 v[72:73], v[78:79], v[72:73]
	s_nop 0
	v_lshl_or_b32 v83, v84, 16, v83
	v_cvt_pk_bf16_f32 v72, v72, v73
	v_pk_mul_f32 v[74:75], v[74:75], v[86:87]
	s_nop 0
	v_cvt_pk_bf16_f32 v71, v74, v75
	ds_write_b16 v140, v72 offset:816
	ds_write_b16_d16_hi v140, v72 offset:952
	ds_write_b16 v140, v71 offset:5168
	ds_write_b16_d16_hi v140, v71 offset:5304
	v_lshl_add_u64 v[72:73], v[134:135], 0, s[28:29]
	v_lshl_add_u64 v[74:75], v[72:73], 0, s[26:27]
	v_lshl_add_u64 v[172:173], v[74:75], 0, s[98:99]
	s_waitcnt vmcnt(51)
	v_mov_b32_e32 v74, v188
	global_load_ushort v188, v[172:173], off offset:1024
	s_mul_i32 s28, s25, 0xe00
	v_lshl_add_u64 v[174:175], v[72:73], 0, s[98:99]
	s_waitcnt vmcnt(51)
	v_mov_b32_e32 v85, v225
	global_load_ushort v225, v[174:175], off offset:512
	s_ashr_i32 s29, s28, 31
	v_lshl_add_u64 v[86:87], v[134:135], 0, s[28:29]
	v_lshl_add_u64 v[88:89], v[86:87], 0, s[26:27]
	s_add_i32 s25, s25, s65
	s_mul_i32 s28, s25, 0xe00
	s_ashr_i32 s29, s28, 31
	s_add_i32 s25, s25, s65
	s_nop 0
	v_lshlrev_b32_e32 v74, 16, v74
	v_max_f32_e32 v74, v74, v74
	v_max_f32_e32 v74, 0xc2700000, v74
	v_mul_f32_e32 v74, 0xbfb8aa3b, v74
	v_exp_f32_e32 v74, v74
	s_nop 0
	v_add_f32_e32 v75, 1.0, v74
	v_rcp_f32_e32 v76, v75
	v_lshl_add_u64 v[172:173], v[88:89], 0, s[98:99]
	s_waitcnt vmcnt(51)
	v_mov_b32_e32 v75, v189
	global_load_ushort v189, v[172:173], off offset:1024
	s_nop 0
	v_lshl_add_u64 v[174:175], v[72:73], 0, s[98:99]
	s_waitcnt vmcnt(51)
	v_mov_b32_e32 v72, v209
	global_load_ushort v209, v[174:175], off
	s_nop 0
	v_lshl_add_u64 v[172:173], v[86:87], 0, s[98:99]
	s_waitcnt vmcnt(51)
	v_mov_b32_e32 v73, v210
	global_load_ushort v210, v[172:173], off
	v_fma_f32 v78, v133, v76, v130
	v_mul_f32_e32 v78, v79, v78
	v_max_f32_e32 v79, 0xda24260, v78
	v_rcp_f32_e32 v88, v79
	v_lshl_add_u64 v[174:175], v[86:87], 0, s[98:99]
	s_waitcnt vmcnt(45)
	v_mov_b32_e32 v86, v245
	global_load_ushort v245, v[174:175], off offset:512
	s_nop 0
	v_lshlrev_b32_e32 v72, 16, v72
	v_lshlrev_b32_e32 v75, 16, v75
	v_max_f32_e32 v75, v75, v75
	v_max_f32_e32 v75, 0xc2700000, v75
	v_mul_f32_e32 v75, 0xbfb8aa3b, v75
	v_exp_f32_e32 v75, v75
	s_nop 0
	v_lshlrev_b32_e32 v73, 16, v73
	v_add_f32_e32 v77, 1.0, v75
	v_rcp_f32_e32 v77, v77
	s_nop 0
	v_fma_f32 v89, v133, v77, v130
	v_mul_f32_e32 v79, v78, v89
	v_pk_mul_f32 v[90:91], v[78:79], v[72:73]
	v_max_f32_e32 v72, 0xda24260, v79
	v_rcp_f32_e32 v89, v72
	v_pk_mul_f32 v[72:73], v[138:139], v[74:75]
	v_lshl_add_u64 v[74:75], v[134:135], 0, s[28:29]
	v_pk_mul_f32 v[72:73], v[72:73], v[76:77]
	v_lshl_add_u64 v[76:77], v[74:75], 0, s[26:27]
	v_pk_mul_f32 v[72:73], v[72:73], v[88:89]
	s_mul_i32 s28, s25, 0xe00
	v_cvt_pk_bf16_f32 v72, v72, v73
	v_cvt_pk_bf16_f32 v73, v90, v91
	ds_write_b16 v140, v73 offset:1088
	ds_write_b16_d16_hi v140, v73 offset:1224
	ds_write_b16 v140, v72 offset:5440
	ds_write_b16_d16_hi v140, v72 offset:5576
	v_lshl_add_u64 v[172:173], v[76:77], 0, s[98:99]
	s_nop 0
	v_mov_b32_e32 v73, v190
	global_load_ushort v190, v[172:173], off offset:1024
	v_lshl_add_u64 v[174:175], v[74:75], 0, s[98:99]
	s_nop 0
	v_mov_b32_e32 v87, v246
	global_load_ushort v246, v[174:175], off offset:512
	s_ashr_i32 s29, s28, 31
	v_lshl_add_u64 v[90:91], v[134:135], 0, s[28:29]
	v_lshl_add_u64 v[92:93], v[90:91], 0, s[26:27]
	v_lshl_add_u64 v[172:173], v[92:93], 0, s[98:99]
	s_nop 0
	v_mov_b32_e32 v77, v191
	global_load_ushort v191, v[172:173], off offset:1024
	s_add_i32 s25, s25, s65
	s_mul_i32 s28, s25, 0xe00
	s_ashr_i32 s29, s28, 31
	s_add_i32 s25, s25, s65
	s_nop 0
	v_lshlrev_b32_e32 v73, 16, v73
	v_max_f32_e32 v73, v73, v73
	v_max_f32_e32 v73, 0xc2700000, v73
	v_mul_f32_e32 v73, 0xbfb8aa3b, v73
	v_exp_f32_e32 v76, v73
	s_nop 0
	v_lshlrev_b32_e32 v77, 16, v77
	v_max_f32_e32 v77, v77, v77
	v_max_f32_e32 v77, 0xc2700000, v77
	v_add_f32_e32 v73, 1.0, v76
	v_mul_f32_e32 v77, 0xbfb8aa3b, v77
	v_rcp_f32_e32 v88, v73
	v_exp_f32_e32 v77, v77
	v_fma_f32 v73, v133, v88, v130
	v_add_f32_e32 v78, 1.0, v77
	v_rcp_f32_e32 v89, v78
	v_mul_f32_e32 v78, v79, v73
	v_max_f32_e32 v73, 0xda24260, v78
	v_rcp_f32_e32 v92, v73
	v_lshl_add_u64 v[174:175], v[74:75], 0, s[98:99]
	s_nop 0
	v_mov_b32_e32 v73, v211
	global_load_ushort v211, v[174:175], off
	s_nop 0
	v_lshl_add_u64 v[172:173], v[90:91], 0, s[98:99]
	s_nop 0
	v_mov_b32_e32 v74, v212
	global_load_ushort v212, v[172:173], off
	v_fma_f32 v93, v133, v89, v130
	v_mul_f32_e32 v79, v78, v93
	v_pk_mul_f32 v[76:77], v[138:139], v[76:77]
	s_nop 0
	v_lshlrev_b32_e32 v75, 16, v74
	v_lshlrev_b32_e32 v74, 16, v73
	v_max_f32_e32 v73, 0xda24260, v79
	v_rcp_f32_e32 v93, v73
	v_pk_mul_f32 v[74:75], v[78:79], v[74:75]
	v_pk_mul_f32 v[76:77], v[76:77], v[88:89]
	v_cvt_pk_bf16_f32 v74, v74, v75
	v_pk_mul_f32 v[76:77], v[76:77], v[92:93]
	v_lshl_add_u64 v[174:175], v[90:91], 0, s[98:99]
	s_nop 0
	v_mov_b32_e32 v88, v248
	global_load_ushort v248, v[174:175], off offset:512
	v_cvt_pk_bf16_f32 v73, v76, v77
	ds_write_b16 v140, v74 offset:1360
	ds_write_b16_d16_hi v140, v74 offset:1496
	ds_write_b16 v140, v73 offset:5712
	ds_write_b16_d16_hi v140, v73 offset:5848
	v_lshl_add_u64 v[74:75], v[134:135], 0, s[28:29]
	v_lshl_add_u64 v[76:77], v[74:75], 0, s[26:27]
	v_lshl_add_u64 v[172:173], v[76:77], 0, s[98:99]
	s_waitcnt vmcnt(51)
	v_mov_b32_e32 v76, v192
	global_load_ushort v192, v[172:173], off offset:1024
	s_mul_i32 s28, s25, 0xe00
	v_lshl_add_u64 v[174:175], v[74:75], 0, s[98:99]
	s_waitcnt vmcnt(51)
	v_mov_b32_e32 v89, v249
	global_load_ushort v249, v[174:175], off offset:512
	s_ashr_i32 s29, s28, 31
	v_lshl_add_u64 v[92:93], v[134:135], 0, s[28:29]
	v_lshl_add_u64 v[94:95], v[92:93], 0, s[26:27]
	s_add_i32 s25, s25, s65
	s_mul_i32 s28, s25, 0xe00
	s_ashr_i32 s29, s28, 31
	s_add_i32 s25, s25, s65
	s_nop 0
	v_lshlrev_b32_e32 v76, 16, v76
	v_max_f32_e32 v76, v76, v76
	v_max_f32_e32 v76, 0xc2700000, v76
	v_mul_f32_e32 v76, 0xbfb8aa3b, v76
	v_exp_f32_e32 v76, v76
	s_nop 0
	v_add_f32_e32 v77, 1.0, v76
	v_rcp_f32_e32 v90, v77
	v_lshl_add_u64 v[172:173], v[94:95], 0, s[98:99]
	s_waitcnt vmcnt(51)
	v_mov_b32_e32 v77, v193
	global_load_ushort v193, v[172:173], off offset:1024
	s_nop 0
	v_lshl_add_u64 v[174:175], v[74:75], 0, s[98:99]
	s_waitcnt vmcnt(51)
	v_mov_b32_e32 v74, v213
	global_load_ushort v213, v[174:175], off
	s_nop 0
	v_lshl_add_u64 v[172:173], v[92:93], 0, s[98:99]
	s_waitcnt vmcnt(51)
	v_mov_b32_e32 v75, v214
	global_load_ushort v214, v[172:173], off
	v_lshl_add_u64 v[174:175], v[92:93], 0, s[98:99]
	s_waitcnt vmcnt(51)
	v_mov_b32_e32 v108, v250
	global_load_ushort v250, v[174:175], off offset:512
	v_fma_f32 v78, v133, v90, v130
	v_mul_f32_e32 v78, v79, v78
	v_max_f32_e32 v79, 0xda24260, v78
	v_rcp_f32_e32 v94, v79
	s_nop 0
	v_lshlrev_b32_e32 v74, 16, v74
	v_lshlrev_b32_e32 v77, 16, v77
	v_max_f32_e32 v77, v77, v77
	v_max_f32_e32 v77, 0xc2700000, v77
	v_mul_f32_e32 v77, 0xbfb8aa3b, v77
	v_exp_f32_e32 v77, v77
	s_nop 0
	v_lshlrev_b32_e32 v75, 16, v75
	v_add_f32_e32 v91, 1.0, v77
	v_rcp_f32_e32 v91, v91
	s_nop 0
	v_fma_f32 v95, v133, v91, v130
	v_mul_f32_e32 v79, v78, v95
	v_pk_mul_f32 v[96:97], v[78:79], v[74:75]
	v_max_f32_e32 v74, 0xda24260, v79
	v_rcp_f32_e32 v95, v74
	v_pk_mul_f32 v[74:75], v[138:139], v[76:77]
	v_lshl_add_u64 v[76:77], v[134:135], 0, s[28:29]
	v_pk_mul_f32 v[74:75], v[74:75], v[90:91]
	v_lshl_add_u64 v[90:91], v[76:77], 0, s[26:27]
	v_pk_mul_f32 v[74:75], v[74:75], v[94:95]
	s_mul_i32 s28, s25, 0xe00
	v_cvt_pk_bf16_f32 v74, v74, v75
	v_cvt_pk_bf16_f32 v75, v96, v97
	ds_write_b16 v140, v75 offset:1632
	ds_write_b16_d16_hi v140, v75 offset:1768
	ds_write_b16 v140, v74 offset:5984
	ds_write_b16_d16_hi v140, v74 offset:6120
	v_lshl_add_u64 v[172:173], v[90:91], 0, s[98:99]
	s_waitcnt vmcnt(51)
	v_mov_b32_e32 v75, v194
	global_load_ushort v194, v[172:173], off offset:1024
	s_ashr_i32 s29, s28, 31
	v_lshl_add_u64 v[94:95], v[134:135], 0, s[28:29]
	v_lshl_add_u64 v[96:97], v[94:95], 0, s[26:27]
	v_lshl_add_u64 v[174:175], v[96:97], 0, s[98:99]
	s_waitcnt vmcnt(50)
	v_mov_b32_e32 v78, v195
	global_load_ushort v195, v[174:175], off offset:1024
	v_lshl_add_u64 v[172:173], v[76:77], 0, s[98:99]
	s_nop 0
	v_mov_b32_e32 v109, v251
	global_load_ushort v251, v[172:173], off offset:512
	s_add_i32 s25, s25, s65
	s_mul_i32 s28, s25, 0xe00
	s_ashr_i32 s29, s28, 31
	s_add_i32 s25, s25, s65
	s_nop 0
	v_lshlrev_b32_e32 v75, 16, v75
	v_max_f32_e32 v75, v75, v75
	v_max_f32_e32 v75, 0xc2700000, v75
	v_mul_f32_e32 v75, 0xbfb8aa3b, v75
	v_exp_f32_e32 v90, v75
	s_nop 0
	v_lshlrev_b32_e32 v78, 16, v78
	v_max_f32_e32 v78, v78, v78
	v_max_f32_e32 v78, 0xc2700000, v78
	v_add_f32_e32 v75, 1.0, v90
	v_mul_f32_e32 v78, 0xbfb8aa3b, v78
	v_rcp_f32_e32 v92, v75
	v_exp_f32_e32 v91, v78
	v_fma_f32 v75, v133, v92, v130
	v_add_f32_e32 v78, 1.0, v91
	v_rcp_f32_e32 v93, v78
	v_mul_f32_e32 v78, v79, v75
	v_max_f32_e32 v75, 0xda24260, v78
	v_rcp_f32_e32 v96, v75
	v_lshl_add_u64 v[174:175], v[76:77], 0, s[98:99]
	s_waitcnt vmcnt(51)
	v_mov_b32_e32 v75, v215
	global_load_ushort v215, v[174:175], off
	s_nop 0
	v_lshl_add_u64 v[172:173], v[94:95], 0, s[98:99]
	s_waitcnt vmcnt(51)
	v_mov_b32_e32 v76, v216
	global_load_ushort v216, v[172:173], off
	v_fma_f32 v97, v133, v93, v130
	v_mul_f32_e32 v79, v78, v97
	v_pk_mul_f32 v[90:91], v[138:139], v[90:91]
	v_lshl_add_u64 v[174:175], v[94:95], 0, s[98:99]
	s_waitcnt vmcnt(51)
	v_mov_b32_e32 v110, v252
	global_load_ushort v252, v[174:175], off offset:512
	v_pk_mul_f32 v[90:91], v[90:91], v[92:93]
	s_nop 0
	v_lshlrev_b32_e32 v77, 16, v76
	v_lshlrev_b32_e32 v76, 16, v75
	v_max_f32_e32 v75, 0xda24260, v79
	v_rcp_f32_e32 v97, v75
	v_pk_mul_f32 v[76:77], v[78:79], v[76:77]
	v_pk_mul_f32 v[90:91], v[90:91], v[96:97]
	v_cvt_pk_bf16_f32 v76, v76, v77
	v_cvt_pk_bf16_f32 v75, v90, v91
	ds_write_b16 v140, v76 offset:1904
	ds_write_b16_d16_hi v140, v76 offset:2040
	ds_write_b16 v140, v75 offset:6256
	ds_write_b16_d16_hi v140, v75 offset:6392
	v_lshl_add_u64 v[76:77], v[134:135], 0, s[28:29]
	s_mul_i32 s28, s25, 0xe00
	v_lshl_add_u64 v[90:91], v[76:77], 0, s[26:27]
	s_ashr_i32 s29, s28, 31
	v_lshl_add_u64 v[172:173], v[90:91], 0, s[100:101]
	s_waitcnt vmcnt(47)
	v_mov_b32_e32 v78, v180
	global_load_ushort v180, v[172:173], off offset:1024
	v_lshl_add_u64 v[174:175], v[76:77], 0, s[100:101]
	s_waitcnt vmcnt(47)
	v_mov_b32_e32 v111, v217
	global_load_ushort v217, v[174:175], off offset:512
	v_lshl_add_u64 v[94:95], v[134:135], 0, s[28:29]
	v_lshl_add_u64 v[96:97], v[94:95], 0, s[26:27]
	v_lshl_add_u64 v[172:173], v[96:97], 0, s[100:101]
	s_waitcnt vmcnt(47)
	v_mov_b32_e32 v91, v181
	global_load_ushort v181, v[172:173], off offset:1024
	s_nop 0
	v_lshl_add_u64 v[174:175], v[76:77], 0, s[100:101]
	s_waitcnt vmcnt(46)
	v_mov_b32_e32 v76, v196
	global_load_ushort v196, v[174:175], off
	s_nop 0
	v_lshl_add_u64 v[172:173], v[94:95], 0, s[100:101]
	s_nop 0
	v_mov_b32_e32 v77, v197
	global_load_ushort v197, v[172:173], off
	s_add_i32 s25, s25, s65
	s_mul_i32 s28, s25, 0xe00
	s_ashr_i32 s29, s28, 31
	s_add_i32 s25, s25, s65
	s_nop 0
	v_lshlrev_b32_e32 v78, 16, v78
	v_max_f32_e32 v78, v78, v78
	v_max_f32_e32 v78, 0xc2700000, v78
	v_mul_f32_e32 v78, 0xbfb8aa3b, v78
	s_nop 0
	v_lshlrev_b32_e32 v91, 16, v91
	v_max_f32_e32 v91, v91, v91
	v_exp_f32_e32 v90, v78
	v_max_f32_e32 v91, 0xc2700000, v91
	v_mul_f32_e32 v91, 0xbfb8aa3b, v91
	v_exp_f32_e32 v91, v91
	v_add_f32_e32 v78, 1.0, v90
	v_rcp_f32_e32 v92, v78
	s_nop 0
	v_lshlrev_b32_e32 v77, 16, v77
	v_add_f32_e32 v93, 1.0, v91
	v_rcp_f32_e32 v93, v93
	v_fma_f32 v78, v133, v92, v130
	v_mul_f32_e32 v78, v79, v78
	v_max_f32_e32 v79, 0xda24260, v78
	v_fma_f32 v97, v133, v93, v130
	v_rcp_f32_e32 v96, v79
	v_mul_f32_e32 v79, v78, v97
	v_lshlrev_b32_e32 v76, 16, v76
	v_pk_mul_f32 v[98:99], v[78:79], v[76:77]
	v_max_f32_e32 v76, 0xda24260, v79
	v_rcp_f32_e32 v97, v76
	v_pk_mul_f32 v[76:77], v[138:139], v[90:91]
	v_lshl_add_u64 v[90:91], v[134:135], 0, s[28:29]
	v_pk_mul_f32 v[76:77], v[76:77], v[92:93]
	v_lshl_add_u64 v[92:93], v[90:91], 0, s[26:27]
	v_pk_mul_f32 v[76:77], v[76:77], v[96:97]
	s_mul_i32 s28, s25, 0xe00
	v_cvt_pk_bf16_f32 v76, v76, v77
	v_cvt_pk_bf16_f32 v77, v98, v99
	ds_write_b16 v140, v77 offset:2176
	ds_write_b16_d16_hi v140, v77 offset:2312
	ds_write_b16 v140, v76 offset:6528
	ds_write_b16_d16_hi v140, v76 offset:6664
	v_lshl_add_u64 v[174:175], v[92:93], 0, s[100:101]
	s_waitcnt vmcnt(47)
	v_mov_b32_e32 v77, v182
	global_load_ushort v182, v[174:175], off offset:1024
	s_ashr_i32 s29, s28, 31
	v_lshl_add_u64 v[98:99], v[134:135], 0, s[28:29]
	v_lshl_add_u64 v[100:101], v[98:99], 0, s[26:27]
	v_lshl_add_u64 v[172:173], v[100:101], 0, s[100:101]
	s_waitcnt vmcnt(46)
	v_mov_b32_e32 v78, v183
	global_load_ushort v183, v[172:173], off offset:1024
	v_lshl_add_u64 v[174:175], v[90:91], 0, s[100:101]
	s_nop 0
	v_mov_b32_e32 v112, v219
	global_load_ushort v219, v[174:175], off offset:512
	s_add_i32 s25, s25, s65
	s_mul_i32 s28, s25, 0xe00
	s_ashr_i32 s29, s28, 31
	s_add_i32 s25, s25, s65
	s_nop 0
	v_lshlrev_b32_e32 v77, 16, v77
	v_max_f32_e32 v77, v77, v77
	v_max_f32_e32 v77, 0xc2700000, v77
	v_mul_f32_e32 v77, 0xbfb8aa3b, v77
	v_exp_f32_e32 v92, v77
	s_nop 0
	v_lshlrev_b32_e32 v78, 16, v78
	v_max_f32_e32 v78, v78, v78
	v_max_f32_e32 v78, 0xc2700000, v78
	v_add_f32_e32 v77, 1.0, v92
	v_mul_f32_e32 v78, 0xbfb8aa3b, v78
	v_rcp_f32_e32 v96, v77
	v_exp_f32_e32 v93, v78
	v_fma_f32 v77, v133, v96, v130
	v_add_f32_e32 v78, 1.0, v93
	v_rcp_f32_e32 v97, v78
	v_mul_f32_e32 v78, v79, v77
	v_max_f32_e32 v77, 0xda24260, v78
	v_rcp_f32_e32 v100, v77
	v_lshl_add_u64 v[172:173], v[90:91], 0, s[100:101]
	s_waitcnt vmcnt(46)
	v_mov_b32_e32 v77, v198
	global_load_ushort v198, v[172:173], off
	s_nop 0
	v_lshl_add_u64 v[174:175], v[98:99], 0, s[100:101]
	s_nop 0
	v_mov_b32_e32 v90, v199
	global_load_ushort v199, v[174:175], off
	v_fma_f32 v101, v133, v97, v130
	v_mul_f32_e32 v79, v78, v101
	v_pk_mul_f32 v[92:93], v[138:139], v[92:93]
	s_nop 0
	v_lshlrev_b32_e32 v91, 16, v90
	v_lshlrev_b32_e32 v90, 16, v77
	v_max_f32_e32 v77, 0xda24260, v79
	v_rcp_f32_e32 v101, v77
	v_pk_mul_f32 v[90:91], v[78:79], v[90:91]
	v_pk_mul_f32 v[92:93], v[92:93], v[96:97]
	v_cvt_pk_bf16_f32 v78, v90, v91
	v_pk_mul_f32 v[92:93], v[92:93], v[100:101]
	v_lshl_add_u64 v[90:91], v[134:135], 0, s[28:29]
	s_mul_i32 s28, s25, 0xe00
	v_cvt_pk_bf16_f32 v77, v92, v93
	ds_write_b16 v140, v78 offset:2448
	ds_write_b16_d16_hi v140, v78 offset:2584
	ds_write_b16 v140, v77 offset:6800
	ds_write_b16_d16_hi v140, v77 offset:6936
	s_ashr_i32 s29, s28, 31
	v_lshl_add_u64 v[92:93], v[90:91], 0, s[26:27]
	v_lshl_add_u64 v[172:173], v[98:99], 0, s[100:101]
	s_waitcnt vmcnt(47)
	v_mov_b32_e32 v113, v220
	global_load_ushort v220, v[172:173], off offset:512
	v_lshl_add_u64 v[174:175], v[94:95], 0, s[100:101]
	s_waitcnt vmcnt(47)
	v_mov_b32_e32 v114, v218
	global_load_ushort v218, v[174:175], off offset:512
	v_lshl_add_u64 v[172:173], v[92:93], 0, s[100:101]
	s_waitcnt vmcnt(47)
	v_mov_b32_e32 v78, v184
	global_load_ushort v184, v[172:173], off offset:1024
	v_lshl_add_u64 v[96:97], v[134:135], 0, s[28:29]
	v_lshl_add_u64 v[98:99], v[96:97], 0, s[26:27]
	v_lshl_add_u64 v[174:175], v[90:91], 0, s[100:101]
	s_waitcnt vmcnt(47)
	v_mov_b32_e32 v115, v221
	global_load_ushort v221, v[174:175], off offset:512
	v_lshl_add_u64 v[172:173], v[98:99], 0, s[100:101]
	s_waitcnt vmcnt(47)
	v_mov_b32_e32 v93, v185
	global_load_ushort v185, v[172:173], off offset:1024
	s_nop 0
	v_lshl_add_u64 v[174:175], v[90:91], 0, s[100:101]
	s_waitcnt vmcnt(47)
	v_mov_b32_e32 v90, v200
	global_load_ushort v200, v[174:175], off
	s_nop 0
	v_lshl_add_u64 v[172:173], v[96:97], 0, s[100:101]
	s_waitcnt vmcnt(47)
	v_mov_b32_e32 v91, v206
	global_load_ushort v206, v[172:173], off
	s_add_i32 s25, s25, s65
	s_mul_i32 s28, s25, 0xe00
	s_ashr_i32 s29, s28, 31
	s_add_i32 s25, s25, s65
	s_nop 0
	v_lshlrev_b32_e32 v78, 16, v78
	v_max_f32_e32 v78, v78, v78
	v_max_f32_e32 v78, 0xc2700000, v78
	v_mul_f32_e32 v78, 0xbfb8aa3b, v78
	s_nop 0
	v_lshlrev_b32_e32 v93, 16, v93
	v_max_f32_e32 v93, v93, v93
	v_exp_f32_e32 v92, v78
	v_max_f32_e32 v93, 0xc2700000, v93
	v_mul_f32_e32 v93, 0xbfb8aa3b, v93
	v_exp_f32_e32 v93, v93
	v_add_f32_e32 v78, 1.0, v92
	v_rcp_f32_e32 v94, v78
	s_nop 0
	v_lshlrev_b32_e32 v91, 16, v91
	v_add_f32_e32 v95, 1.0, v93
	v_rcp_f32_e32 v95, v95
	v_fma_f32 v78, v133, v94, v130
	v_mul_f32_e32 v78, v79, v78
	v_max_f32_e32 v79, 0xda24260, v78
	v_fma_f32 v99, v133, v95, v130
	v_rcp_f32_e32 v98, v79
	v_mul_f32_e32 v79, v78, v99
	v_lshlrev_b32_e32 v90, 16, v90
	v_pk_mul_f32 v[90:91], v[78:79], v[90:91]
	v_max_f32_e32 v78, 0xda24260, v79
	v_rcp_f32_e32 v99, v78
	v_pk_mul_f32 v[92:93], v[138:139], v[92:93]
	v_cvt_pk_bf16_f32 v90, v90, v91
	v_pk_mul_f32 v[92:93], v[92:93], v[94:95]
	s_nop 0
	v_pk_mul_f32 v[92:93], v[92:93], v[98:99]
	s_nop 0
	v_cvt_pk_bf16_f32 v78, v92, v93
	ds_write_b16 v140, v90 offset:2720
	ds_write_b16_d16_hi v140, v90 offset:2856
	ds_write_b16 v140, v78 offset:7072
	ds_write_b16_d16_hi v140, v78 offset:7208
	v_lshl_add_u64 v[90:91], v[134:135], 0, s[28:29]
	v_lshl_add_u64 v[92:93], v[90:91], 0, s[26:27]
	v_lshl_add_u64 v[174:175], v[92:93], 0, s[100:101]
	s_waitcnt vmcnt(46)
	v_mov_b32_e32 v92, v186
	global_load_ushort v186, v[174:175], off offset:1024
	s_mul_i32 s28, s25, 0xe00
	v_lshl_add_u64 v[172:173], v[90:91], 0, s[100:101]
	s_waitcnt vmcnt(46)
	v_mov_b32_e32 v116, v223
	global_load_ushort v223, v[172:173], off offset:512
	s_ashr_i32 s29, s28, 31
	v_lshl_add_u64 v[98:99], v[134:135], 0, s[28:29]
	v_lshl_add_u64 v[100:101], v[98:99], 0, s[26:27]
	s_add_i32 s25, s25, s65
	s_mul_i32 s28, s25, 0xe00
	s_ashr_i32 s29, s28, 31
	s_add_i32 s25, s25, s65
	s_nop 0
	v_lshlrev_b32_e32 v92, 16, v92
	v_max_f32_e32 v92, v92, v92
	v_max_f32_e32 v92, 0xc2700000, v92
	v_mul_f32_e32 v92, 0xbfb8aa3b, v92
	v_exp_f32_e32 v92, v92
	s_nop 0
	v_add_f32_e32 v93, 1.0, v92
	v_rcp_f32_e32 v94, v93
	v_lshl_add_u64 v[174:175], v[100:101], 0, s[100:101]
	s_waitcnt vmcnt(46)
	v_mov_b32_e32 v93, v187
	global_load_ushort v187, v[174:175], off offset:1024
	v_fma_f32 v102, v133, v94, v130
	v_mul_f32_e32 v100, v79, v102
	v_max_f32_e32 v79, 0xda24260, v100
	v_rcp_f32_e32 v102, v79
	v_lshl_add_u64 v[172:173], v[90:91], 0, s[100:101]
	s_waitcnt vmcnt(46)
	v_mov_b32_e32 v79, v207
	global_load_ushort v207, v[172:173], off
	s_nop 0
	v_lshl_add_u64 v[174:175], v[98:99], 0, s[100:101]
	s_waitcnt vmcnt(46)
	v_mov_b32_e32 v90, v208
	global_load_ushort v208, v[174:175], off
	s_nop 0
	v_lshlrev_b32_e32 v93, 16, v93
	v_max_f32_e32 v93, v93, v93
	v_max_f32_e32 v93, 0xc2700000, v93
	v_mul_f32_e32 v93, 0xbfb8aa3b, v93
	v_exp_f32_e32 v93, v93
	s_nop 0
	v_lshlrev_b32_e32 v91, 16, v90
	v_add_f32_e32 v95, 1.0, v93
	v_rcp_f32_e32 v95, v95
	v_lshlrev_b32_e32 v90, 16, v79
	v_pk_mul_f32 v[92:93], v[138:139], v[92:93]
	v_fma_f32 v101, v133, v95, v130
	v_mul_f32_e32 v101, v100, v101
	v_max_f32_e32 v79, 0xda24260, v101
	v_rcp_f32_e32 v103, v79
	v_pk_mul_f32 v[90:91], v[100:101], v[90:91]
	v_pk_mul_f32 v[92:93], v[92:93], v[94:95]
	v_cvt_pk_bf16_f32 v90, v90, v91
	v_pk_mul_f32 v[92:93], v[92:93], v[102:103]
	s_nop 0
	v_cvt_pk_bf16_f32 v79, v92, v93
	ds_write_b16 v140, v90 offset:2992
	ds_write_b16_d16_hi v140, v90 offset:3128
	ds_write_b16 v140, v79 offset:7344
	ds_write_b16_d16_hi v140, v79 offset:7480
	v_lshl_add_u64 v[90:91], v[134:135], 0, s[28:29]
	v_lshl_add_u64 v[92:93], v[90:91], 0, s[26:27]
	v_lshl_add_u64 v[172:173], v[98:99], 0, s[100:101]
	s_waitcnt vmcnt(46)
	v_mov_b32_e32 v117, v224
	global_load_ushort v224, v[172:173], off offset:512
	v_lshl_add_u64 v[174:175], v[96:97], 0, s[100:101]
	s_nop 0
	v_mov_b32_e32 v118, v222
	global_load_ushort v222, v[174:175], off offset:512
	s_nop 0
	v_lshl_add_u64 v[172:173], v[92:93], 0, s[100:101]
	s_waitcnt vmcnt(47)
	v_mov_b32_e32 v92, v188
	global_load_ushort v188, v[172:173], off offset:1024
	s_mul_i32 s28, s25, 0xe00
	s_ashr_i32 s29, s28, 31
	v_lshl_add_u64 v[96:97], v[134:135], 0, s[28:29]
	v_lshl_add_u64 v[98:99], v[96:97], 0, s[26:27]
	v_lshl_add_u64 v[174:175], v[90:91], 0, s[100:101]
	s_waitcnt vmcnt(47)
	v_mov_b32_e32 v119, v225
	global_load_ushort v225, v[174:175], off offset:512
	s_add_i32 s25, s25, s65
	s_mul_i32 s28, s25, 0xe00
	s_ashr_i32 s29, s28, 31
	s_add_i32 s25, s25, s65
	s_nop 0
	v_lshlrev_b32_e32 v92, 16, v92
	v_max_f32_e32 v92, v92, v92
	v_max_f32_e32 v92, 0xc2700000, v92
	v_mul_f32_e32 v92, 0xbfb8aa3b, v92
	v_exp_f32_e32 v92, v92
	s_nop 0
	v_add_f32_e32 v93, 1.0, v92
	v_rcp_f32_e32 v94, v93
	v_lshl_add_u64 v[172:173], v[98:99], 0, s[100:101]
	s_waitcnt vmcnt(47)
	v_mov_b32_e32 v93, v189
	global_load_ushort v189, v[172:173], off offset:1024
	s_nop 0
	v_lshl_add_u64 v[174:175], v[90:91], 0, s[100:101]
	s_waitcnt vmcnt(47)
	v_mov_b32_e32 v90, v209
	global_load_ushort v209, v[174:175], off
	s_nop 0
	v_lshl_add_u64 v[172:173], v[96:97], 0, s[100:101]
	s_waitcnt vmcnt(47)
	v_mov_b32_e32 v91, v210
	global_load_ushort v210, v[172:173], off
	v_fma_f32 v100, v133, v94, v130
	v_mul_f32_e32 v98, v101, v100
	v_max_f32_e32 v100, 0xda24260, v98
	v_rcp_f32_e32 v100, v100
	s_nop 0
	v_lshlrev_b32_e32 v93, 16, v93
	v_max_f32_e32 v93, v93, v93
	v_max_f32_e32 v93, 0xc2700000, v93
	v_mul_f32_e32 v93, 0xbfb8aa3b, v93
	v_exp_f32_e32 v93, v93
	s_nop 0
	v_lshlrev_b32_e32 v91, 16, v91
	v_lshlrev_b32_e32 v90, 16, v90
	v_add_f32_e32 v95, 1.0, v93
	v_rcp_f32_e32 v95, v95
	s_nop 0
	v_fma_f32 v99, v133, v95, v130
	v_mul_f32_e32 v99, v98, v99
	v_pk_mul_f32 v[102:103], v[98:99], v[90:91]
	v_max_f32_e32 v90, 0xda24260, v99
	v_rcp_f32_e32 v101, v90
	v_pk_mul_f32 v[90:91], v[138:139], v[92:93]
	v_lshl_add_u64 v[92:93], v[134:135], 0, s[28:29]
	v_pk_mul_f32 v[90:91], v[90:91], v[94:95]
	v_lshl_add_u64 v[94:95], v[92:93], 0, s[26:27]
	v_pk_mul_f32 v[90:91], v[90:91], v[100:101]
	s_mul_i32 s28, s25, 0xe00
	v_cvt_pk_bf16_f32 v90, v90, v91
	v_cvt_pk_bf16_f32 v91, v102, v103
	ds_write_b16 v140, v91 offset:3264
	ds_write_b16_d16_hi v140, v91 offset:3400
	ds_write_b16 v140, v90 offset:7616
	ds_write_b16_d16_hi v140, v90 offset:7752
	v_lshl_add_u64 v[174:175], v[94:95], 0, s[100:101]
	s_waitcnt vmcnt(46)
	v_mov_b32_e32 v91, v190
	global_load_ushort v190, v[174:175], off offset:1024
	v_lshl_add_u64 v[172:173], v[92:93], 0, s[100:101]
	s_waitcnt vmcnt(46)
	v_mov_b32_e32 v120, v246
	global_load_ushort v246, v[172:173], off offset:512
	s_ashr_i32 s29, s28, 31
	v_lshl_add_u64 v[102:103], v[134:135], 0, s[28:29]
	v_lshl_add_u64 v[104:105], v[102:103], 0, s[26:27]
	v_lshl_add_u64 v[174:175], v[104:105], 0, s[100:101]
	s_waitcnt vmcnt(46)
	v_mov_b32_e32 v95, v191
	global_load_ushort v191, v[174:175], off offset:1024
	s_add_i32 s25, s25, s65
	s_mul_i32 s28, s25, 0xe00
	s_ashr_i32 s29, s28, 31
	s_add_i32 s25, s25, s65
	s_nop 0
	v_lshlrev_b32_e32 v91, 16, v91
	v_max_f32_e32 v91, v91, v91
	v_max_f32_e32 v91, 0xc2700000, v91
	v_mul_f32_e32 v91, 0xbfb8aa3b, v91
	v_exp_f32_e32 v94, v91
	s_nop 0
	v_lshlrev_b32_e32 v95, 16, v95
	v_max_f32_e32 v95, v95, v95
	v_max_f32_e32 v95, 0xc2700000, v95
	v_add_f32_e32 v91, 1.0, v94
	v_mul_f32_e32 v95, 0xbfb8aa3b, v95
	v_rcp_f32_e32 v100, v91
	v_exp_f32_e32 v95, v95
	v_fma_f32 v91, v133, v100, v130
	v_add_f32_e32 v98, 1.0, v95
	v_rcp_f32_e32 v101, v98
	v_mul_f32_e32 v98, v99, v91
	v_max_f32_e32 v91, 0xda24260, v98
	v_rcp_f32_e32 v104, v91
	v_lshl_add_u64 v[172:173], v[92:93], 0, s[100:101]
	s_waitcnt vmcnt(46)
	v_mov_b32_e32 v91, v211
	global_load_ushort v211, v[172:173], off
	s_nop 0
	v_lshl_add_u64 v[174:175], v[102:103], 0, s[100:101]
	s_waitcnt vmcnt(46)
	v_mov_b32_e32 v92, v212
	global_load_ushort v212, v[174:175], off
	v_fma_f32 v105, v133, v101, v130
	v_mul_f32_e32 v99, v98, v105
	v_pk_mul_f32 v[94:95], v[138:139], v[94:95]
	s_nop 0
	v_lshlrev_b32_e32 v93, 16, v92
	v_lshlrev_b32_e32 v92, 16, v91
	v_max_f32_e32 v91, 0xda24260, v99
	v_rcp_f32_e32 v105, v91
	v_pk_mul_f32 v[92:93], v[98:99], v[92:93]
	v_pk_mul_f32 v[94:95], v[94:95], v[100:101]
	v_cvt_pk_bf16_f32 v92, v92, v93
	v_pk_mul_f32 v[94:95], v[94:95], v[104:105]
	s_nop 0
	v_cvt_pk_bf16_f32 v91, v94, v95
	ds_write_b16 v140, v92 offset:3536
	ds_write_b16_d16_hi v140, v92 offset:3672
	ds_write_b16 v140, v91 offset:7888
	ds_write_b16_d16_hi v140, v91 offset:8024
	v_lshl_add_u64 v[92:93], v[134:135], 0, s[28:29]
	v_lshl_add_u64 v[94:95], v[92:93], 0, s[26:27]
	v_lshl_add_u64 v[172:173], v[102:103], 0, s[100:101]
	s_waitcnt vmcnt(46)
	v_mov_b32_e32 v121, v248
	global_load_ushort v248, v[172:173], off offset:512
	v_lshl_add_u64 v[174:175], v[96:97], 0, s[100:101]
	s_nop 0
	v_mov_b32_e32 v122, v245
	global_load_ushort v245, v[174:175], off offset:512
	s_nop 0
	v_lshl_add_u64 v[172:173], v[94:95], 0, s[100:101]
	s_waitcnt vmcnt(47)
	v_mov_b32_e32 v94, v192
	global_load_ushort v192, v[172:173], off offset:1024
	s_mul_i32 s28, s25, 0xe00
	s_ashr_i32 s29, s28, 31
	v_lshl_add_u64 v[100:101], v[134:135], 0, s[28:29]
	v_lshl_add_u64 v[102:103], v[100:101], 0, s[26:27]
	v_lshl_add_u64 v[174:175], v[92:93], 0, s[100:101]
	s_waitcnt vmcnt(47)
	v_mov_b32_e32 v123, v249
	global_load_ushort v249, v[174:175], off offset:512
	s_add_i32 s25, s25, s65
	s_mul_i32 s28, s25, 0xe00
	s_ashr_i32 s29, s28, 31
	s_add_i32 s25, s25, s65
	s_nop 0
	v_lshlrev_b32_e32 v94, 16, v94
	v_max_f32_e32 v94, v94, v94
	v_max_f32_e32 v94, 0xc2700000, v94
	v_mul_f32_e32 v94, 0xbfb8aa3b, v94
	v_exp_f32_e32 v94, v94
	s_nop 0
	v_add_f32_e32 v95, 1.0, v94
	v_rcp_f32_e32 v96, v95
	v_lshl_add_u64 v[172:173], v[102:103], 0, s[100:101]
	s_waitcnt vmcnt(47)
	v_mov_b32_e32 v95, v193
	global_load_ushort v193, v[172:173], off offset:1024
	s_nop 0
	v_lshl_add_u64 v[174:175], v[92:93], 0, s[100:101]
	s_waitcnt vmcnt(47)
	v_mov_b32_e32 v92, v213
	global_load_ushort v213, v[174:175], off
	s_nop 0
	v_lshl_add_u64 v[172:173], v[100:101], 0, s[100:101]
	s_waitcnt vmcnt(47)
	v_mov_b32_e32 v93, v214
	global_load_ushort v214, v[172:173], off
	v_lshl_add_u64 v[174:175], v[100:101], 0, s[100:101]
	s_waitcnt vmcnt(47)
	v_mov_b32_e32 v132, v250
	global_load_ushort v250, v[174:175], off offset:512
	v_fma_f32 v98, v133, v96, v130
	v_mul_f32_e32 v98, v99, v98
	v_max_f32_e32 v99, 0xda24260, v98
	v_rcp_f32_e32 v102, v99
	s_nop 0
	v_lshlrev_b32_e32 v95, 16, v95
	v_max_f32_e32 v95, v95, v95
	v_max_f32_e32 v95, 0xc2700000, v95
	v_mul_f32_e32 v95, 0xbfb8aa3b, v95
	v_exp_f32_e32 v95, v95
	s_nop 0
	v_lshlrev_b32_e32 v93, 16, v93
	v_lshlrev_b32_e32 v92, 16, v92
	v_add_f32_e32 v97, 1.0, v95
	v_rcp_f32_e32 v97, v97
	s_nop 0
	v_fma_f32 v103, v133, v97, v130
	v_mul_f32_e32 v99, v98, v103
	v_pk_mul_f32 v[104:105], v[98:99], v[92:93]
	v_max_f32_e32 v92, 0xda24260, v99
	v_rcp_f32_e32 v103, v92
	v_pk_mul_f32 v[92:93], v[138:139], v[94:95]
	v_lshl_add_u64 v[94:95], v[134:135], 0, s[28:29]
	v_pk_mul_f32 v[92:93], v[92:93], v[96:97]
	v_lshl_add_u64 v[96:97], v[94:95], 0, s[26:27]
	v_pk_mul_f32 v[92:93], v[92:93], v[102:103]
	s_mul_i32 s28, s25, 0xe00
	v_cvt_pk_bf16_f32 v92, v92, v93
	v_cvt_pk_bf16_f32 v93, v104, v105
	ds_write_b16 v140, v93 offset:3808
	ds_write_b16_d16_hi v140, v93 offset:3944
	ds_write_b16 v140, v92 offset:8160
	ds_write_b16_d16_hi v140, v92 offset:8296
	v_lshl_add_u64 v[172:173], v[96:97], 0, s[100:101]
	s_waitcnt vmcnt(47)
	v_mov_b32_e32 v93, v194
	global_load_ushort v194, v[172:173], off offset:1024
	v_lshl_add_u64 v[174:175], v[94:95], 0, s[100:101]
	s_waitcnt vmcnt(46)
	v_mov_b32_e32 v159, v251
	global_load_ushort v251, v[174:175], off offset:512
	s_ashr_i32 s29, s28, 31
	v_lshl_add_u64 v[102:103], v[134:135], 0, s[28:29]
	v_lshl_add_u64 v[104:105], v[102:103], 0, s[26:27]
	v_lshl_add_u64 v[172:173], v[104:105], 0, s[100:101]
	s_nop 0
	v_mov_b32_e32 v97, v195
	global_load_ushort v195, v[172:173], off offset:1024
	v_lshl_or_b32 v105, v110, 16, v109
	s_cmpk_eq_i32 s24, 0x80
	s_nop 0
	v_lshlrev_b32_e32 v93, 16, v93
	v_max_f32_e32 v93, v93, v93
	v_max_f32_e32 v93, 0xc2700000, v93
	v_mul_f32_e32 v93, 0xbfb8aa3b, v93
	v_exp_f32_e32 v96, v93
	s_nop 0
	v_lshlrev_b32_e32 v97, 16, v97
	v_max_f32_e32 v97, v97, v97
	v_max_f32_e32 v97, 0xc2700000, v97
	v_add_f32_e32 v93, 1.0, v96
	v_rcp_f32_e32 v100, v93
	v_mul_f32_e32 v97, 0xbfb8aa3b, v97
	v_exp_f32_e32 v97, v97
	v_fma_f32 v93, v133, v100, v130
	v_mul_f32_e32 v106, v99, v93
	v_add_f32_e32 v98, 1.0, v97
	v_max_f32_e32 v93, 0xda24260, v106
	v_rcp_f32_e32 v101, v98
	v_rcp_f32_e32 v98, v93
	v_lshl_add_u64 v[174:175], v[94:95], 0, s[100:101]
	s_waitcnt vmcnt(47)
	v_mov_b32_e32 v93, v215
	global_load_ushort v215, v[174:175], off
	s_nop 0
	v_lshl_add_u64 v[172:173], v[102:103], 0, s[100:101]
	s_waitcnt vmcnt(47)
	v_mov_b32_e32 v94, v216
	global_load_ushort v216, v[172:173], off
	v_pk_mul_f32 v[96:97], v[138:139], v[96:97]
	v_fma_f32 v104, v133, v101, v130
	v_mul_f32_e32 v107, v106, v104
	v_pk_mul_f32 v[96:97], v[96:97], v[100:101]
	v_lshl_or_b32 v101, v117, 16, v116
	v_lshl_or_b32 v100, v118, 16, v115
	v_lshl_or_b32 v104, v108, 16, v89
	v_cvt_pk_bf16_f32 v115, v30, v31
	s_nop 0
	v_lshlrev_b32_e32 v95, 16, v94
	v_lshlrev_b32_e32 v94, 16, v93
	v_pk_mul_f32 v[94:95], v[106:107], v[94:95]
	v_max_f32_e32 v93, 0xda24260, v107
	v_cvt_pk_bf16_f32 v94, v94, v95
	v_lshl_add_u64 v[174:175], v[102:103], 0, s[100:101]
	s_waitcnt vmcnt(47)
	v_mov_b32_e32 v95, v252
	global_load_ushort v252, v[174:175], off offset:512
	v_rcp_f32_e32 v99, v93
	v_lshl_or_b32 v103, v88, 16, v87
	v_lshl_or_b32 v102, v86, 16, v85
	v_pk_mul_f32 v[96:97], v[96:97], v[98:99]
	s_nop 0
	v_cvt_pk_bf16_f32 v93, v96, v97
	ds_write_b16 v140, v94 offset:4080
	ds_write_b16_d16_hi v140, v94 offset:4216
	ds_write_b16 v140, v93 offset:8432
	ds_write_b16_d16_hi v140, v93 offset:8568
	v_lshl_or_b32 v96, v132, 16, v123
	v_lshl_or_b32 v94, v122, 16, v119
	v_lshl_or_b32 v99, v113, 16, v112
	v_lshl_or_b32 v98, v114, 16, v111
	v_add_u32_e32 v112, v145, v142
	v_add_u32_e32 v116, 0x3800, v112
	v_cvt_pk_bf16_f32 v113, v14, v15
	v_cvt_pk_bf16_f32 v114, v28, v29
	s_nop 0
	v_lshl_or_b32 v97, v95, 16, v159
	v_lshl_or_b32 v95, v121, 16, v120
	ds_write_b128 v141, v[68:71] offset:8704
	ds_write_b128 v141, v[80:83] offset:12800
	ds_write_b128 v141, v[72:75] offset:8720
	ds_write_b128 v141, v[102:105] offset:12816
	ds_write_b128 v141, v[76:79] offset:8736
	ds_write_b128 v141, v[98:101] offset:12832
	ds_write_b128 v141, v[90:93] offset:8752
	ds_write_b128 v141, v[94:97] offset:12848
	ds_write_b32 v151, v107 offset:16896
	s_waitcnt lgkmcnt(0)
	ds_read2_b64 v[84:87], v152 offset1:4
	ds_read2_b64 v[68:71], v0 offset0:32 offset1:36
	ds_read2_b64 v[96:99], v152 offset0:8 offset1:12
	ds_read2_b64 v[72:75], v0 offset0:40 offset1:44
	v_add_u32_e32 v0, 0x800, v152
	ds_read2_b64 v[100:103], v0 offset0:16 offset1:20
	ds_read2_b64 v[76:79], v1 offset0:48 offset1:52
	ds_read2_b64 v[104:107], v0 offset0:24 offset1:28
	ds_read2_b64 v[80:83], v1 offset0:56 offset1:60
	s_waitcnt lgkmcnt(6)
	v_mfma_f32_16x16x32_bf16 v[88:91], v[68:71], v[84:87], 0
	v_cvt_pk_bf16_f32 v92, v40, v41
	v_cvt_pk_bf16_f32 v93, v42, v43
	v_cvt_pk_bf16_f32 v94, v56, v57
	s_waitcnt lgkmcnt(3)
	v_mfma_f32_16x16x32_bf16 v[68:71], v[68:71], v[100:103], 0
	v_cvt_pk_bf16_f32 v95, v58, v59
	s_waitcnt lgkmcnt(2)
	v_mfma_f32_16x16x32_bf16 v[76:79], v[76:79], v[100:103], 0
	v_mfma_f32_16x16x32_bf16 v[88:91], v[72:75], v[96:99], v[88:91]
	s_waitcnt lgkmcnt(1)
	v_mfma_f32_16x16x32_bf16 v[68:71], v[72:75], v[104:107], v[68:71]
	s_waitcnt lgkmcnt(0)
	v_mfma_f32_16x16x32_bf16 v[76:79], v[80:83], v[104:107], v[76:79]
	s_nop 3
	v_cndmask_b32_e64 v1, v91, 0, vcc
	v_cndmask_b32_e64 v3, v90, 0, s[42:43]
	v_cndmask_b32_e64 v0, v89, 0, s[40:41]
	v_cndmask_b32_e64 v80, v88, 0, s[38:39]
	v_add_u32_e32 v88, 0x3000, v112
	v_cvt_pk_bf16_f32 v0, v80, v0
	v_cvt_pk_bf16_f32 v1, v3, v1
	v_mov_b32_e32 v3, v2
	v_cvt_pk_bf16_f32 v108, v68, v69
	v_cvt_pk_bf16_f32 v109, v70, v71
	ds_read2_b64 v[68:71], v88 offset0:64 offset1:68
	v_cndmask_b32_e64 v79, v79, 0, vcc
	v_cndmask_b32_e64 v78, v78, 0, s[42:43]
	v_cndmask_b32_e64 v77, v77, 0, s[40:41]
	v_cndmask_b32_e64 v76, v76, 0, s[38:39]
	v_cvt_pk_bf16_f32 v110, v76, v77
	v_cvt_pk_bf16_f32 v111, v78, v79
	s_waitcnt lgkmcnt(0)
	v_mfma_f32_16x16x32_bf16 v[72:75], v[0:3], v[68:71], 0
	v_cvt_pk_bf16_f32 v76, v4, v5
	v_cvt_pk_bf16_f32 v77, v6, v7
	v_cvt_pk_bf16_f32 v78, v20, v21
	v_mfma_f32_16x16x32_bf16 v[68:71], v[108:111], v[68:71], 0
	v_cvt_pk_bf16_f32 v79, v22, v23
	v_cvt_pk_bf16_f32 v89, v10, v11
	v_cvt_pk_bf16_f32 v90, v24, v25
	v_mfma_f32_16x16x32_bf16 v[72:75], v[84:87], v[76:79], v[72:75]
	v_cvt_pk_bf16_f32 v91, v26, v27
	v_cvt_pk_bf16_f32 v112, v12, v13
	v_mfma_f32_16x16x32_bf16 v[68:71], v[100:103], v[76:79], v[68:71]
	v_cvt_pk_bf16_f32 v76, v36, v37
	v_cvt_pk_bf16_f32 v77, v38, v39
	v_cvt_pk_bf16_f32 v78, v52, v53
	v_cvt_pk_bf16_f32 v79, v54, v55
	s_nop 1
	v_mfma_f32_16x16x32_bf16 v[80:83], v[96:99], v[76:79], v[72:75]
	s_nop 2
	ds_read2_b64 v[72:75], v88 offset0:192 offset1:196
	v_mfma_f32_16x16x32_bf16 v[68:71], v[104:107], v[76:79], v[68:71]
	v_cvt_pk_bf16_f32 v88, v8, v9
	s_waitcnt lgkmcnt(0)
	v_mfma_f32_16x16x32_bf16 v[76:79], v[0:3], v[72:75], 0
	v_mfma_f32_16x16x32_bf16 v[72:75], v[108:111], v[72:75], 0
	v_mfma_f32_16x16x32_bf16 v[76:79], v[84:87], v[88:91], v[76:79]
	v_mfma_f32_16x16x32_bf16 v[72:75], v[100:103], v[88:91], v[72:75]
	v_mfma_f32_16x16x32_bf16 v[88:91], v[96:99], v[92:95], v[76:79]
	s_nop 5
	ds_read2_b64 v[76:79], v116 offset0:64 offset1:68
	v_mfma_f32_16x16x32_bf16 v[72:75], v[104:107], v[92:95], v[72:75]
	s_waitcnt lgkmcnt(0)
	v_mfma_f32_16x16x32_bf16 v[92:95], v[0:3], v[76:79], 0
	v_mfma_f32_16x16x32_bf16 v[76:79], v[108:111], v[76:79], 0
	v_mfma_f32_16x16x32_bf16 v[92:95], v[84:87], v[112:115], v[92:95]
	v_mfma_f32_16x16x32_bf16 v[76:79], v[100:103], v[112:115], v[76:79]
	v_cvt_pk_bf16_f32 v112, v44, v45
	v_cvt_pk_bf16_f32 v113, v46, v47
	v_cvt_pk_bf16_f32 v114, v60, v61
	v_cvt_pk_bf16_f32 v115, v62, v63
	s_nop 1
	v_mfma_f32_16x16x32_bf16 v[92:95], v[96:99], v[112:115], v[92:95]
	v_mfma_f32_16x16x32_bf16 v[76:79], v[104:107], v[112:115], v[76:79]
	ds_read2_b64 v[112:115], v116 offset0:192 offset1:196
	s_waitcnt lgkmcnt(0)
	v_mfma_f32_16x16x32_bf16 v[116:119], v[0:3], v[112:115], 0
	v_add_u32_e32 v0, v146, v143
	v_mfma_f32_16x16x32_bf16 v[108:111], v[108:111], v[112:115], 0
	v_cvt_pk_bf16_f32 v112, v16, v17
	v_cvt_pk_bf16_f32 v113, v18, v19
	v_cvt_pk_bf16_f32 v114, v32, v33
	v_cvt_pk_bf16_f32 v115, v34, v35
	s_nop 1
	v_mfma_f32_16x16x32_bf16 v[84:87], v[84:87], v[112:115], v[116:119]
	v_mfma_f32_16x16x32_bf16 v[100:103], v[100:103], v[112:115], v[108:111]
	s_nop 2
	v_cvt_pk_bf16_f32 v108, v48, v49
	v_cvt_pk_bf16_f32 v109, v50, v51
	v_cvt_pk_bf16_f32 v110, v64, v65
	v_cvt_pk_bf16_f32 v111, v66, v67
	s_nop 1
	v_mfma_f32_16x16x32_bf16 v[96:99], v[96:99], v[108:111], v[84:87]
	v_mfma_f32_16x16x32_bf16 v[84:87], v[104:107], v[108:111], v[100:103]
	ds_read_b128 v[160:163], v0 offset:8704
	ds_read_b128 v[116:119], v0 offset:12800
	ds_read_b128 v[164:167], v0 offset:9728
	ds_read_b128 v[112:115], v0 offset:13824
	ds_read_b128 v[120:123], v0 offset:10752
	ds_read_b128 v[108:111], v0 offset:14848
	ds_read_b128 v[100:103], v0 offset:11776
	ds_read_b128 v[104:107], v0 offset:15872
	ds_read_b128 v[168:171], v146 offset:16896
	v_cvt_pk_bf16_f32 v0, v80, s0
	s_waitcnt lgkmcnt(7)
	v_mfma_f32_16x16x32_bf16 v[4:7], v[160:163], v[116:119], v[4:7]
	s_waitcnt lgkmcnt(5)
	v_mfma_f32_16x16x32_bf16 v[8:11], v[160:163], v[112:115], v[8:11]
	s_waitcnt lgkmcnt(3)
	v_mfma_f32_16x16x32_bf16 v[12:15], v[160:163], v[108:111], v[12:15]
	s_waitcnt lgkmcnt(0)
	s_nop 2
	v_pk_mul_f32 v[6:7], v[170:171], v[6:7]
	v_pk_mul_f32 v[4:5], v[168:169], v[4:5]
	v_pk_mul_f32 v[10:11], v[170:171], v[10:11]
	v_mfma_f32_16x16x32_bf16 v[16:19], v[160:163], v[104:107], v[16:19]
	ds_read_b128 v[160:163], v146 offset:16960
	v_pk_mul_f32 v[8:9], v[168:169], v[8:9]
	v_pk_mul_f32 v[14:15], v[170:171], v[14:15]
	v_mfma_f32_16x16x32_bf16 v[20:23], v[164:167], v[116:119], v[20:23]
	v_mul_f32_e64 v12, v168, v12
	v_mul_f32_e64 v13, v169, v13
	s_nop 1
	v_pk_mul_f32 v[18:19], v[170:171], v[18:19]
	v_pk_mul_f32 v[16:17], v[168:169], v[16:17]
	v_mfma_f32_16x16x32_bf16 v[24:27], v[164:167], v[112:115], v[24:27]
	v_mfma_f32_16x16x32_bf16 v[28:31], v[164:167], v[108:111], v[28:31]
	v_mfma_f32_16x16x32_bf16 v[32:35], v[164:167], v[104:107], v[32:35]
	v_mfma_f32_16x16x32_bf16 v[36:39], v[120:123], v[116:119], v[36:39]
	v_mfma_f32_16x16x32_bf16 v[40:43], v[120:123], v[112:115], v[40:43]
	v_mfma_f32_16x16x32_bf16 v[44:47], v[120:123], v[108:111], v[44:47]
	v_mfma_f32_16x16x32_bf16 v[48:51], v[120:123], v[104:107], v[48:51]
	ds_read_b128 v[120:123], v146 offset:17088
	s_waitcnt lgkmcnt(1)
	v_pk_mul_f32 v[22:23], v[162:163], v[22:23]
	v_pk_mul_f32 v[20:21], v[160:161], v[20:21]
	v_pk_mul_f32 v[26:27], v[162:163], v[26:27]
	v_pk_mul_f32 v[24:25], v[160:161], v[24:25]
	v_pk_mul_f32 v[30:31], v[162:163], v[30:31]
	v_pk_mul_f32 v[28:29], v[160:161], v[28:29]
	v_pk_mul_f32 v[34:35], v[162:163], v[34:35]
	v_pk_mul_f32 v[32:33], v[160:161], v[32:33]
	ds_read_b128 v[160:163], v146 offset:17024
	ds_write_b16 v153, v0
	v_cvt_pk_bf16_f32 v0, v88, s0
	ds_write_b16 v153, v0 offset:32
	v_cvt_pk_bf16_f32 v0, v92, s0
	ds_write_b16 v153, v0 offset:64
	v_cvt_pk_bf16_f32 v0, v96, s0
	ds_write_b16 v153, v0 offset:96
	v_cvt_pk_bf16_f32 v0, v81, s0
	ds_write_b16 v154, v0
	v_cvt_pk_bf16_f32 v0, v89, s0
	ds_write_b16 v154, v0 offset:32
	v_cvt_pk_bf16_f32 v0, v93, s0
	ds_write_b16 v154, v0 offset:64
	v_cvt_pk_bf16_f32 v0, v97, s0
	ds_write_b16 v154, v0 offset:96
	v_cvt_pk_bf16_f32 v0, v82, s0
	ds_write_b16 v154, v0 offset:136
	v_cvt_pk_bf16_f32 v0, v90, s0
	ds_write_b16 v154, v0 offset:168
	v_cvt_pk_bf16_f32 v0, v94, s0
	ds_write_b16 v154, v0 offset:200
	v_cvt_pk_bf16_f32 v0, v98, s0
	ds_write_b16 v154, v0 offset:232
	v_cvt_pk_bf16_f32 v0, v83, s0
	ds_write_b16 v154, v0 offset:272
	v_cvt_pk_bf16_f32 v0, v91, s0
	ds_write_b16 v154, v0 offset:304
	v_cvt_pk_bf16_f32 v0, v95, s0
	ds_write_b16 v154, v0 offset:336
	v_cvt_pk_bf16_f32 v0, v99, s0
	ds_write_b16 v154, v0 offset:368
	v_cvt_pk_bf16_f32 v0, v68, s0
	ds_write_b16 v154, v0 offset:2040
	v_cvt_pk_bf16_f32 v0, v72, s0
	ds_write_b16 v154, v0 offset:2072
	v_cvt_pk_bf16_f32 v0, v76, s0
	ds_write_b16 v154, v0 offset:2104
	v_cvt_pk_bf16_f32 v0, v84, s0
	ds_write_b16 v154, v0 offset:2136
	v_cvt_pk_bf16_f32 v0, v69, s0
	ds_write_b16 v154, v0 offset:2176
	v_cvt_pk_bf16_f32 v0, v73, s0
	ds_write_b16 v154, v0 offset:2208
	v_cvt_pk_bf16_f32 v0, v77, s0
	ds_write_b16 v154, v0 offset:2240
	v_cvt_pk_bf16_f32 v0, v85, s0
	ds_write_b16 v154, v0 offset:2272
	v_cvt_pk_bf16_f32 v0, v70, s0
	ds_write_b16 v154, v0 offset:2312
	v_cvt_pk_bf16_f32 v0, v74, s0
	ds_write_b16 v154, v0 offset:2344
	v_cvt_pk_bf16_f32 v0, v78, s0
	ds_write_b16 v154, v0 offset:2376
	v_cvt_pk_bf16_f32 v0, v86, s0
	ds_write_b16 v154, v0 offset:2408
	v_cvt_pk_bf16_f32 v0, v71, s0
	ds_write_b16 v154, v0 offset:2448
	v_cvt_pk_bf16_f32 v0, v75, s0
	ds_write_b16 v154, v0 offset:2480
	v_cvt_pk_bf16_f32 v0, v79, s0
	ds_write_b16 v154, v0 offset:2512
	v_cvt_pk_bf16_f32 v0, v87, s0
	ds_write_b16 v154, v0 offset:2544
	s_waitcnt lgkmcnt(0)
	ds_read2_b64 v[68:71], v155 offset1:1
	v_add_u32_e32 v0, s3, v147
	v_ashrrev_i32_e32 v1, 31, v0
	v_lshl_add_u64 v[0:1], s[56:57], 0, v[0:1]
	v_lshlrev_b64 v[0:1], 9, v[0:1]
	v_lshl_add_u64 v[0:1], v[136:137], 0, v[0:1]
	s_waitcnt lgkmcnt(0)
	global_store_dwordx4 v[0:1], v[68:71], off
	ds_read2_b64 v[68:71], v156 offset1:1
	v_add_u32_e32 v0, s3, v148
	v_ashrrev_i32_e32 v1, 31, v0
	v_lshl_add_u64 v[0:1], s[56:57], 0, v[0:1]
	v_lshlrev_b64 v[0:1], 9, v[0:1]
	v_lshl_add_u64 v[0:1], v[136:137], 0, v[0:1]
	s_waitcnt lgkmcnt(0)
	global_store_dwordx4 v[0:1], v[68:71], off
	ds_read2_b64 v[68:71], v157 offset1:1
	v_add_u32_e32 v0, s3, v149
	v_ashrrev_i32_e32 v1, 31, v0
	v_lshl_add_u64 v[0:1], s[56:57], 0, v[0:1]
	v_lshlrev_b64 v[0:1], 9, v[0:1]
	v_lshl_add_u64 v[0:1], v[136:137], 0, v[0:1]
	s_waitcnt lgkmcnt(0)
	global_store_dwordx4 v[0:1], v[68:71], off
	ds_read2_b64 v[68:71], v158 offset1:1
	v_add_u32_e32 v0, s3, v150
	v_ashrrev_i32_e32 v1, 31, v0
	v_lshl_add_u64 v[0:1], s[56:57], 0, v[0:1]
	v_lshlrev_b64 v[0:1], 9, v[0:1]
	v_mfma_f32_16x16x32_bf16 v[52:55], v[100:103], v[116:119], v[52:55]
	v_lshl_add_u64 v[0:1], v[136:137], 0, v[0:1]
	s_waitcnt lgkmcnt(0)
	global_store_dwordx4 v[0:1], v[68:71], off
	s_waitcnt lgkmcnt(0)
	v_mfma_f32_16x16x32_bf16 v[56:59], v[100:103], v[112:115], v[56:59]
	v_mul_f32_e64 v38, v162, v38
	v_mul_f32_e64 v39, v163, v39
	v_pk_mul_f32 v[36:37], v[160:161], v[36:37]
	v_pk_mul_f32 v[42:43], v[162:163], v[42:43]
	v_mfma_f32_16x16x32_bf16 v[60:63], v[100:103], v[108:111], v[60:63]
	v_mul_f32_e64 v40, v160, v40
	v_mul_f32_e64 v41, v161, v41
	v_pk_mul_f32 v[46:47], v[162:163], v[46:47]
	v_pk_mul_f32 v[44:45], v[160:161], v[44:45]
	v_mfma_f32_16x16x32_bf16 v[64:67], v[100:103], v[104:107], v[64:67]
	v_mul_f32_e64 v50, v162, v50
	v_mul_f32_e64 v51, v163, v51
	v_pk_mul_f32 v[48:49], v[160:161], v[48:49]
	v_pk_mul_f32 v[54:55], v[122:123], v[54:55]
	v_pk_mul_f32 v[52:53], v[120:121], v[52:53]
	v_pk_mul_f32 v[58:59], v[122:123], v[58:59]
	v_pk_mul_f32 v[56:57], v[120:121], v[56:57]
	v_pk_mul_f32 v[62:63], v[122:123], v[62:63]
	v_pk_mul_f32 v[60:61], v[120:121], v[60:61]
	v_pk_mul_f32 v[66:67], v[122:123], v[66:67]
	v_pk_mul_f32 v[64:65], v[120:121], v[64:65]
	s_cbranch_scc0 .LBB0_687
	s_lshl_b32 s3, s69, 7
	s_waitcnt vmcnt(0)
	s_barrier
	s_load_dwordx2 s[24:25], s[44:45], 0x48
	s_and_b32 s3, s3, 0x3f80
	v_or_b32_e32 v1, s3, v144
	v_and_b32_e32 v3, 64, v204
	v_or_b32_e32 v134, s56, v1
	v_xor_b32_e32 v1, 1, v204
	v_add_u32_e32 v3, 64, v3
	s_lshl_b64 s[28:29], s[48:49], 2
	v_cmp_lt_i32_e32 vcc, v1, v3
	s_waitcnt lgkmcnt(0)
	s_add_u32 s24, s24, s28
	s_addc_u32 s25, s25, s29
	v_cndmask_b32_e32 v130, v204, v1, vcc
	v_xor_b32_e32 v1, 2, v204
	s_lshl_b32 s28, s55, 2
	v_cmp_lt_i32_e32 vcc, v1, v3
	s_add_u32 s24, s24, s28
	s_addc_u32 s25, s25, 0
	v_cndmask_b32_e32 v131, v204, v1, vcc
	v_xor_b32_e32 v1, 4, v204
	v_lshlrev_b32_e32 v0, 2, v124
	v_mov_b32_e32 v135, s57
	s_mov_b32 s55, s27
	v_cmp_lt_i32_e32 vcc, v1, v3
	v_lshl_add_u64 v[12:13], v[126:127], 0, s[54:55]
	v_lshl_add_u64 v[14:15], v[128:129], 0, s[54:55]
	v_cndmask_b32_e32 v3, v204, v1, vcc
	global_load_dwordx4 v[4:7], v0, s[24:25] offset:16
	global_load_dwordx4 v[8:11], v0, s[24:25]
	v_lshlrev_b64 v[0:1], 9, v[134:135]
	v_lshl_add_u64 v[16:17], v[12:13], 0, v[0:1]
	v_lshl_add_u64 v[0:1], v[14:15], 0, v[0:1]
	global_load_dwordx4 v[100:103], v[16:17], off
	global_load_dwordx4 v[104:107], v[0:1], off
	v_mov_b64_e32 v[0:1], s[50:51]
	v_mad_u64_u32 v[0:1], s[24:25], v134, s83, v[0:1]
	v_mad_i32_i24 v1, s57, v243, v1
	v_lshl_add_u64 v[16:17], v[0:1], 0, s[54:55]
	v_lshlrev_b32_e32 v0, 1, v124
	v_mov_b32_e32 v1, v2
	v_lshl_add_u64 v[122:123], v[16:17], 0, v[0:1]
	global_load_dwordx4 v[96:99], v[122:123], off offset:2048
	v_or_b32_e32 v120, 8, v134
	v_mov_b32_e32 v121, s57
	v_lshlrev_b64 v[16:17], 9, v[120:121]
	v_lshl_add_u64 v[18:19], v[12:13], 0, v[16:17]
	v_lshl_add_u64 v[16:17], v[14:15], 0, v[16:17]
	s_movk_i32 s3, 0x7000
	global_load_dwordx4 v[92:95], v[18:19], off
	global_load_dwordx4 v[88:91], v[16:17], off
	v_add_co_u32_e32 v16, vcc, s3, v122
	v_or_b32_e32 v118, 16, v134
	s_nop 0
	v_addc_co_u32_e32 v17, vcc, 0, v123, vcc
	v_mov_b32_e32 v119, s57
	global_load_dwordx4 v[84:87], v[16:17], off offset:2048
	v_lshlrev_b64 v[16:17], 9, v[118:119]
	v_lshl_add_u64 v[18:19], v[12:13], 0, v[16:17]
	v_lshl_add_u64 v[16:17], v[14:15], 0, v[16:17]
	s_mov_b32 s3, 0xe000
	global_load_dwordx4 v[76:79], v[18:19], off
	global_load_dwordx4 v[80:83], v[16:17], off
	v_add_co_u32_e32 v16, vcc, s3, v122
	v_or_b32_e32 v116, 24, v134
	s_nop 0
	v_addc_co_u32_e32 v17, vcc, 0, v123, vcc
	v_mov_b32_e32 v117, s57
	global_load_dwordx4 v[72:75], v[16:17], off offset:2048
	v_lshlrev_b64 v[16:17], 9, v[116:117]
	v_lshl_add_u64 v[18:19], v[12:13], 0, v[16:17]
	v_lshl_add_u64 v[16:17], v[14:15], 0, v[16:17]
	s_mov_b32 s3, 0x15000
	global_load_dwordx4 v[68:71], v[18:19], off
	global_load_dwordx4 v[64:67], v[16:17], off
	v_add_co_u32_e32 v16, vcc, s3, v122
	v_or_b32_e32 v114, 32, v134
	s_nop 0
	v_addc_co_u32_e32 v17, vcc, 0, v123, vcc
	v_mov_b32_e32 v115, s57
	global_load_dwordx4 v[60:63], v[16:17], off offset:2048
	v_lshlrev_b64 v[16:17], 9, v[114:115]
	v_lshl_add_u64 v[18:19], v[12:13], 0, v[16:17]
	v_lshl_add_u64 v[16:17], v[14:15], 0, v[16:17]
	s_mov_b32 s3, 0x1c000
	global_load_dwordx4 v[52:55], v[18:19], off
	global_load_dwordx4 v[56:59], v[16:17], off
	v_add_co_u32_e32 v16, vcc, s3, v122
	v_or_b32_e32 v112, 40, v134
	s_nop 0
	v_addc_co_u32_e32 v17, vcc, 0, v123, vcc
	v_mov_b32_e32 v113, s57
	global_load_dwordx4 v[48:51], v[16:17], off offset:2048
	v_lshlrev_b64 v[16:17], 9, v[112:113]
	v_lshl_add_u64 v[18:19], v[12:13], 0, v[16:17]
	v_lshl_add_u64 v[16:17], v[14:15], 0, v[16:17]
	s_mov_b32 s3, 0x23000
	global_load_dwordx4 v[44:47], v[18:19], off
	global_load_dwordx4 v[40:43], v[16:17], off
	v_add_co_u32_e32 v16, vcc, s3, v122
	v_or_b32_e32 v110, 48, v134
	s_nop 0
	v_addc_co_u32_e32 v17, vcc, 0, v123, vcc
	v_mov_b32_e32 v111, s57
	global_load_dwordx4 v[36:39], v[16:17], off offset:2048
	v_lshlrev_b64 v[16:17], 9, v[110:111]
	v_lshl_add_u64 v[18:19], v[12:13], 0, v[16:17]
	v_lshl_add_u64 v[16:17], v[14:15], 0, v[16:17]
	s_mov_b32 s3, 0x2a000
	v_or_b32_e32 v108, 56, v134
	v_mov_b32_e32 v109, s57
	global_load_dwordx4 v[28:31], v[18:19], off
	global_load_dwordx4 v[32:35], v[16:17], off
	v_add_co_u32_e32 v16, vcc, s3, v122
	v_lshlrev_b64 v[20:21], 9, v[108:109]
	s_nop 0
	v_addc_co_u32_e32 v17, vcc, 0, v123, vcc
	v_lshl_add_u64 v[12:13], v[12:13], 0, v[20:21]
	global_load_dwordx4 v[24:27], v[16:17], off offset:2048
	s_mov_b32 s3, 0x31000
	global_load_dwordx4 v[16:19], v[12:13], off
	v_lshl_add_u64 v[12:13], v[14:15], 0, v[20:21]
	global_load_dwordx4 v[20:23], v[12:13], off
	v_add_co_u32_e32 v12, vcc, s3, v122
	v_lshlrev_b32_e32 v146, 2, v130
	s_nop 0
	v_addc_co_u32_e32 v13, vcc, 0, v123, vcc
	v_lshlrev_b32_e32 v145, 2, v131
	s_waitcnt vmcnt(22)
	v_lshlrev_b32_e32 v122, 16, v103
	v_and_b32_e32 v123, 0xffff0000, v103
	s_waitcnt vmcnt(21)
	v_lshlrev_b32_e32 v130, 16, v107
	v_and_b32_e32 v131, 0xffff0000, v107
	v_pk_add_f32 v[122:123], v[122:123], v[130:131]
	v_lshlrev_b32_e32 v130, 16, v102
	v_and_b32_e32 v131, 0xffff0000, v102
	v_lshlrev_b32_e32 v102, 16, v106
	v_and_b32_e32 v103, 0xffff0000, v106
	v_pk_add_f32 v[102:103], v[130:131], v[102:103]
	v_mov_b32_e32 v130, v123
	v_mov_b32_e32 v131, v103
	v_mov_b32_e32 v106, v122
	v_mov_b32_e32 v107, v102
	v_pk_mul_f32 v[130:131], v[130:131], v[130:131]
	v_lshlrev_b32_e32 v136, 16, v105
	v_pk_fma_f32 v[132:133], v[106:107], v[106:107], v[130:131]
	s_waitcnt vmcnt(20)
	v_lshlrev_b32_e32 v106, 16, v98
	v_and_b32_e32 v107, 0xffff0000, v98
	v_max_f32_e32 v98, v106, v106
	v_max_f32_e32 v98, 0xc2700000, v98
	v_mul_f32_e32 v98, 0xbfb8aa3b, v98
	v_exp_f32_e32 v98, v98
	v_and_b32_e32 v137, 0xffff0000, v105
	s_waitcnt vmcnt(18)
	v_lshlrev_b32_e32 v140, 16, v91
	v_and_b32_e32 v141, 0xffff0000, v91
	v_add_f32_e32 v98, 1.0, v98
	v_rcp_f32_e32 v130, v98
	v_max_f32_e32 v98, v107, v107
	v_max_f32_e32 v98, 0xc2700000, v98
	v_mul_f32_e32 v98, 0xbfb8aa3b, v98
	v_exp_f32_e32 v98, v98
	v_lshlrev_b32_e32 v142, 16, v89
	v_and_b32_e32 v143, 0xffff0000, v89
	v_lshlrev_b32_e32 v3, 2, v3
	v_add_f32_e32 v98, 1.0, v98
	v_rcp_f32_e32 v131, v98
	s_mov_b32 s24, 0x358637bd
	global_load_dwordx4 v[12:15], v[12:13], off offset:2048
	s_add_i32 s68, s68, s75
	v_pk_mul_f32 v[106:107], v[130:131], v[106:107]
	v_lshlrev_b32_e32 v130, 16, v101
	v_and_b32_e32 v131, 0xffff0000, v101
	v_pk_add_f32 v[130:131], v[130:131], v[136:137]
	v_lshlrev_b32_e32 v136, 16, v97
	v_and_b32_e32 v137, 0xffff0000, v97
	v_max_f32_e32 v97, v136, v136
	v_max_f32_e32 v97, 0xc2700000, v97
	v_mul_f32_e32 v97, 0xbfb8aa3b, v97
	v_exp_f32_e32 v97, v97
	v_and_b32_e32 v101, 0xffff0000, v104
	v_mov_b32_e32 v105, v130
	s_add_i32 s67, s67, s22
	v_add_f32_e32 v97, 1.0, v97
	v_rcp_f32_e32 v138, v97
	v_max_f32_e32 v97, v137, v137
	v_max_f32_e32 v97, 0xc2700000, v97
	v_mul_f32_e32 v97, 0xbfb8aa3b, v97
	v_exp_f32_e32 v97, v97
	s_cmpk_gt_i32 s68, 0x3ff
	v_add_f32_e32 v97, 1.0, v97
	v_rcp_f32_e32 v139, v97
	s_nop 0
	v_pk_mul_f32 v[136:137], v[138:139], v[136:137]
	v_lshlrev_b32_e32 v138, 16, v100
	v_and_b32_e32 v139, 0xffff0000, v100
	v_lshlrev_b32_e32 v100, 16, v104
	v_pk_add_f32 v[100:101], v[138:139], v[100:101]
	v_mov_b32_e32 v139, v131
	v_mov_b32_e32 v138, v101
	v_mov_b32_e32 v104, v100
	v_pk_mul_f32 v[138:139], v[138:139], v[138:139]
	s_nop 0
	v_pk_fma_f32 v[138:139], v[104:105], v[104:105], v[138:139]
	v_lshlrev_b32_e32 v104, 16, v96
	v_and_b32_e32 v105, 0xffff0000, v96
	v_max_f32_e32 v96, v104, v104
	v_max_f32_e32 v97, v105, v105
	v_max_f32_e32 v96, 0xc2700000, v96
	v_max_f32_e32 v97, 0xc2700000, v97
	v_mul_f32_e32 v96, 0xbfb8aa3b, v96
	v_mul_f32_e32 v97, 0xbfb8aa3b, v97
	v_exp_f32_e32 v96, v96
	v_exp_f32_e32 v97, v97
	v_add_f32_e32 v96, 1.0, v96
	v_add_f32_e32 v97, 1.0, v97
	v_rcp_f32_e32 v96, v96
	v_rcp_f32_e32 v97, v97
	s_nop 0
	v_pk_mul_f32 v[104:105], v[96:97], v[104:105]
	v_lshlrev_b32_e32 v96, 16, v99
	v_and_b32_e32 v97, 0xffff0000, v99
	v_max_f32_e32 v98, v96, v96
	v_max_f32_e32 v99, v97, v97
	v_max_f32_e32 v98, 0xc2700000, v98
	v_max_f32_e32 v99, 0xc2700000, v99
	v_mul_f32_e32 v98, 0xbfb8aa3b, v98
	v_mul_f32_e32 v99, 0xbfb8aa3b, v99
	v_exp_f32_e32 v98, v98
	v_exp_f32_e32 v99, v99
	v_add_f32_e32 v98, 1.0, v98
	v_add_f32_e32 v99, 1.0, v99
	v_rcp_f32_e32 v98, v98
	v_rcp_f32_e32 v99, v99
	s_nop 0
	v_pk_mul_f32 v[98:99], v[98:99], v[96:97]
	v_lshlrev_b64 v[96:97], 11, v[134:135]
	v_lshl_add_u64 v[96:97], s[46:47], 0, v[96:97]
	v_lshl_add_u64 v[96:97], v[96:97], 0, s[54:55]
	v_lshl_add_u64 v[134:135], v[96:97], 0, v[0:1]
	v_lshlrev_b32_e32 v96, 16, v95
	v_and_b32_e32 v97, 0xffff0000, v95
	v_pk_add_f32 v[96:97], v[96:97], v[140:141]
	v_lshlrev_b32_e32 v140, 16, v94
	v_and_b32_e32 v141, 0xffff0000, v94
	v_lshlrev_b32_e32 v94, 16, v90
	v_and_b32_e32 v95, 0xffff0000, v90
	v_pk_add_f32 v[90:91], v[140:141], v[94:95]
	v_mov_b32_e32 v140, v97
	v_mov_b32_e32 v141, v91
	v_mov_b32_e32 v94, v96
	v_mov_b32_e32 v95, v90
	v_pk_mul_f32 v[140:141], v[140:141], v[140:141]
	s_nop 0
	v_pk_fma_f32 v[148:149], v[94:95], v[94:95], v[140:141]
	s_waitcnt vmcnt(18)
	v_lshlrev_b32_e32 v94, 16, v86
	v_and_b32_e32 v95, 0xffff0000, v86
	v_max_f32_e32 v86, v94, v94
	v_max_f32_e32 v86, 0xc2700000, v86
	v_mul_f32_e32 v86, 0xbfb8aa3b, v86
	v_exp_f32_e32 v86, v86
	s_nop 0
	v_add_f32_e32 v86, 1.0, v86
	v_rcp_f32_e32 v140, v86
	v_max_f32_e32 v86, v95, v95
	v_max_f32_e32 v86, 0xc2700000, v86
	v_mul_f32_e32 v86, 0xbfb8aa3b, v86
	v_exp_f32_e32 v86, v86
	s_nop 0
	v_add_f32_e32 v86, 1.0, v86
	v_rcp_f32_e32 v141, v86
	s_nop 0
	v_pk_mul_f32 v[94:95], v[140:141], v[94:95]
	v_lshlrev_b32_e32 v140, 16, v93
	v_and_b32_e32 v141, 0xffff0000, v93
	v_pk_add_f32 v[140:141], v[140:141], v[142:143]
	v_lshlrev_b32_e32 v142, 16, v85
	v_and_b32_e32 v143, 0xffff0000, v85
	v_max_f32_e32 v85, v142, v142
	v_max_f32_e32 v85, 0xc2700000, v85
	v_mul_f32_e32 v85, 0xbfb8aa3b, v85
	v_exp_f32_e32 v85, v85
	v_and_b32_e32 v93, 0xffff0000, v88
	v_add_f32_e32 v85, 1.0, v85
	v_rcp_f32_e32 v150, v85
	v_max_f32_e32 v85, v143, v143
	v_max_f32_e32 v85, 0xc2700000, v85
	v_mul_f32_e32 v85, 0xbfb8aa3b, v85
	v_exp_f32_e32 v85, v85
	s_nop 0
	v_add_f32_e32 v85, 1.0, v85
	v_rcp_f32_e32 v151, v85
	s_nop 0
	v_pk_mul_f32 v[142:143], v[150:151], v[142:143]
	v_lshlrev_b32_e32 v150, 16, v92
	v_and_b32_e32 v151, 0xffff0000, v92
	v_lshlrev_b32_e32 v92, 16, v88
	v_pk_add_f32 v[88:89], v[150:151], v[92:93]
	v_mov_b32_e32 v151, v141
	v_mov_b32_e32 v150, v89
	v_mov_b32_e32 v92, v88
	v_mov_b32_e32 v93, v140
	v_pk_mul_f32 v[150:151], v[150:151], v[150:151]
	s_nop 0
	v_pk_fma_f32 v[92:93], v[92:93], v[92:93], v[150:151]
	v_lshlrev_b32_e32 v150, 16, v84
	v_and_b32_e32 v151, 0xffff0000, v84
	v_max_f32_e32 v84, v150, v150
	v_max_f32_e32 v85, v151, v151
	v_max_f32_e32 v84, 0xc2700000, v84
	v_max_f32_e32 v85, 0xc2700000, v85
	v_mul_f32_e32 v84, 0xbfb8aa3b, v84
	v_mul_f32_e32 v85, 0xbfb8aa3b, v85
	v_exp_f32_e32 v84, v84
	v_exp_f32_e32 v85, v85
	v_add_f32_e32 v84, 1.0, v84
	v_add_f32_e32 v85, 1.0, v85
	v_rcp_f32_e32 v84, v84
	v_rcp_f32_e32 v85, v85
	s_nop 0
	v_pk_mul_f32 v[150:151], v[84:85], v[150:151]
	v_mov_b32_e32 v84, v92
	v_mov_b32_e32 v85, v138
	v_mov_b32_e32 v138, v93
	v_pk_add_f32 v[84:85], v[84:85], v[138:139]
	v_mov_b32_e32 v92, v149
	v_mov_b32_e32 v93, v133
	v_pk_add_f32 v[84:85], v[92:93], v[84:85]
	v_mov_b32_e32 v149, v132
	v_pk_add_f32 v[84:85], v[148:149], v[84:85]
	ds_bpermute_b32 v93, v146, v85
	ds_bpermute_b32 v92, v146, v84
	s_waitcnt lgkmcnt(0)
	v_pk_add_f32 v[84:85], v[84:85], v[92:93]
	ds_bpermute_b32 v93, v145, v85
	ds_bpermute_b32 v92, v145, v84
	s_waitcnt lgkmcnt(0)
	v_pk_add_f32 v[84:85], v[84:85], v[92:93]
	ds_bpermute_b32 v93, v3, v85
	ds_bpermute_b32 v92, v3, v84
	s_waitcnt lgkmcnt(0)
	v_pk_add_f32 v[92:93], v[84:85], v[92:93]
	v_mov_b64_e32 v[84:85], s[24:25]
	v_pk_fma_f32 v[92:93], v[92:93], s[80:81], v[84:85] op_sel_hi:[1,0,0]
	s_nop 0
	v_mul_f32_e32 v86, 0x4b800000, v93
	v_cmp_gt_f32_e64 s[38:39], s79, v93
	v_cmp_gt_f32_e32 vcc, s79, v92
	s_nop 0
	v_cndmask_b32_e64 v86, v93, v86, s[38:39]
	v_rsq_f32_e32 v86, v86
	s_nop 0
	v_mul_f32_e32 v93, 0x45800000, v86
	v_cndmask_b32_e64 v86, v86, v93, s[38:39]
	v_pk_mul_f32 v[100:101], v[100:101], v[86:87] op_sel_hi:[1,0]
	v_pk_mul_f32 v[102:103], v[102:103], v[86:87] op_sel_hi:[1,0]
	v_pk_mul_f32 v[100:101], v[8:9], v[100:101]
	v_pk_mul_f32 v[102:103], v[4:5], v[102:103]
	v_pk_mul_f32 v[100:101], v[104:105], v[100:101]
	v_pk_mul_f32 v[104:105], v[130:131], v[86:87] op_sel_hi:[1,0]
	v_cvt_pk_bf16_f32 v100, v100, v101
	v_pk_mul_f32 v[104:105], v[10:11], v[104:105]
	v_pk_mul_f32 v[102:103], v[106:107], v[102:103]
	v_pk_mul_f32 v[104:105], v[136:137], v[104:105]
	v_cvt_pk_bf16_f32 v102, v102, v103
	v_cvt_pk_bf16_f32 v101, v104, v105
	v_pk_mul_f32 v[104:105], v[122:123], v[86:87] op_sel_hi:[1,0]
	v_mul_f32_e32 v86, 0x4b800000, v92
	v_cndmask_b32_e32 v86, v92, v86, vcc
	v_rsq_f32_e32 v86, v86
	v_pk_mul_f32 v[104:105], v[6:7], v[104:105]
	v_mul_f32_e32 v92, 0x45800000, v86
	v_cndmask_b32_e32 v86, v86, v92, vcc
	v_pk_mul_f32 v[88:89], v[88:89], v[86:87] op_sel_hi:[1,0]
	v_pk_mul_f32 v[92:93], v[140:141], v[86:87] op_sel_hi:[1,0]
	v_pk_mul_f32 v[88:89], v[8:9], v[88:89]
	v_pk_mul_f32 v[92:93], v[10:11], v[92:93]
	v_pk_mul_f32 v[90:91], v[90:91], v[86:87] op_sel_hi:[1,0]
	v_pk_mul_f32 v[88:89], v[150:151], v[88:89]
	v_pk_mul_f32 v[92:93], v[142:143], v[92:93]
	v_pk_mul_f32 v[90:91], v[4:5], v[90:91]
	v_cvt_pk_bf16_f32 v88, v88, v89
	v_cvt_pk_bf16_f32 v89, v92, v93
	v_pk_mul_f32 v[90:91], v[94:95], v[90:91]
	v_lshlrev_b32_e32 v92, 16, v87
	v_and_b32_e32 v93, 0xffff0000, v87
	v_cvt_pk_bf16_f32 v90, v90, v91
	v_max_f32_e32 v87, v92, v92
	v_max_f32_e32 v91, v93, v93
	v_max_f32_e32 v87, 0xc2700000, v87
	v_max_f32_e32 v91, 0xc2700000, v91
	v_mul_f32_e32 v87, 0xbfb8aa3b, v87
	v_mul_f32_e32 v91, 0xbfb8aa3b, v91
	v_exp_f32_e32 v87, v87
	v_exp_f32_e32 v91, v91
	v_pk_mul_f32 v[98:99], v[98:99], v[104:105]
	v_add_f32_e32 v87, 1.0, v87
	v_add_f32_e32 v91, 1.0, v91
	v_rcp_f32_e32 v94, v87
	v_rcp_f32_e32 v95, v91
	v_pk_mul_f32 v[86:87], v[96:97], v[86:87] op_sel_hi:[1,0]
	v_cvt_pk_bf16_f32 v103, v98, v99
	v_pk_mul_f32 v[86:87], v[6:7], v[86:87]
	v_pk_mul_f32 v[92:93], v[94:95], v[92:93]
	v_add_co_u32_e64 v98, s[38:39], s81, v134
	v_pk_mul_f32 v[86:87], v[92:93], v[86:87]
	s_waitcnt vmcnt(16)
	v_lshlrev_b32_e32 v92, 16, v81
	v_cvt_pk_bf16_f32 v91, v86, v87
	v_lshlrev_b64 v[86:87], 11, v[120:121]
	v_lshl_add_u64 v[86:87], s[46:47], 0, v[86:87]
	v_lshl_add_u64 v[86:87], v[86:87], 0, s[54:55]
	v_lshl_add_u64 v[86:87], v[86:87], 0, v[0:1]
	v_add_co_u32_e32 v86, vcc, s81, v86
	v_and_b32_e32 v93, 0xffff0000, v81
	s_nop 0
	v_addc_co_u32_e32 v87, vcc, 0, v87, vcc
	global_store_dwordx4 v[86:87], v[88:91], off offset:1024
	v_lshlrev_b32_e32 v86, 16, v79
	v_and_b32_e32 v87, 0xffff0000, v79
	v_lshlrev_b32_e32 v88, 16, v83
	v_and_b32_e32 v89, 0xffff0000, v83
	v_pk_add_f32 v[86:87], v[86:87], v[88:89]
	v_lshlrev_b32_e32 v88, 16, v78
	v_and_b32_e32 v89, 0xffff0000, v78
	v_lshlrev_b32_e32 v78, 16, v82
	v_and_b32_e32 v79, 0xffff0000, v82
	v_pk_add_f32 v[78:79], v[88:89], v[78:79]
	v_mov_b32_e32 v88, v87
	v_mov_b32_e32 v89, v79
	v_mov_b32_e32 v82, v86
	v_mov_b32_e32 v83, v78
	v_pk_mul_f32 v[88:89], v[88:89], v[88:89]
	v_addc_co_u32_e64 v99, s[38:39], 0, v135, s[38:39]
	v_pk_fma_f32 v[90:91], v[82:83], v[82:83], v[88:89]
	s_waitcnt vmcnt(16)
	v_lshlrev_b32_e32 v82, 16, v74
	v_and_b32_e32 v83, 0xffff0000, v74
	v_max_f32_e32 v74, v82, v82
	v_max_f32_e32 v74, 0xc2700000, v74
	v_mul_f32_e32 v74, 0xbfb8aa3b, v74
	v_exp_f32_e32 v74, v74
	global_store_dwordx4 v[98:99], v[100:103], off offset:1024
	s_waitcnt vmcnt(15)
	v_lshlrev_b32_e32 v98, 16, v67
	v_and_b32_e32 v99, 0xffff0000, v67
	v_add_f32_e32 v74, 1.0, v74
	v_rcp_f32_e32 v88, v74
	v_max_f32_e32 v74, v83, v83
	v_max_f32_e32 v74, 0xc2700000, v74
	v_mul_f32_e32 v74, 0xbfb8aa3b, v74
	v_exp_f32_e32 v74, v74
	v_lshlrev_b32_e32 v100, 16, v65
	v_and_b32_e32 v101, 0xffff0000, v65
	v_add_f32_e32 v74, 1.0, v74
	v_rcp_f32_e32 v89, v74
	s_nop 0
	v_pk_mul_f32 v[82:83], v[88:89], v[82:83]
	v_lshlrev_b32_e32 v88, 16, v77
	v_and_b32_e32 v89, 0xffff0000, v77
	v_pk_add_f32 v[88:89], v[88:89], v[92:93]
	v_lshlrev_b32_e32 v92, 16, v73
	v_and_b32_e32 v93, 0xffff0000, v73
	v_max_f32_e32 v73, v92, v92
	v_max_f32_e32 v73, 0xc2700000, v73
	v_mul_f32_e32 v73, 0xbfb8aa3b, v73
	v_exp_f32_e32 v73, v73
	v_and_b32_e32 v77, 0xffff0000, v80
	v_mov_b32_e32 v81, v88
	v_add_f32_e32 v73, 1.0, v73
	v_rcp_f32_e32 v94, v73
	v_max_f32_e32 v73, v93, v93
	v_max_f32_e32 v73, 0xc2700000, v73
	v_mul_f32_e32 v73, 0xbfb8aa3b, v73
	v_exp_f32_e32 v73, v73
	s_nop 0
	v_add_f32_e32 v73, 1.0, v73
	v_rcp_f32_e32 v95, v73
	s_nop 0
	v_pk_mul_f32 v[92:93], v[94:95], v[92:93]
	v_lshlrev_b32_e32 v94, 16, v76
	v_and_b32_e32 v95, 0xffff0000, v76
	v_lshlrev_b32_e32 v76, 16, v80
	v_pk_add_f32 v[76:77], v[94:95], v[76:77]
	v_mov_b32_e32 v95, v89
	v_mov_b32_e32 v94, v77
	v_mov_b32_e32 v80, v76
	v_pk_mul_f32 v[94:95], v[94:95], v[94:95]
	s_nop 0
	v_pk_fma_f32 v[96:97], v[80:81], v[80:81], v[94:95]
	v_lshlrev_b32_e32 v80, 16, v72
	v_and_b32_e32 v81, 0xffff0000, v72
	v_max_f32_e32 v72, v80, v80
	v_max_f32_e32 v73, v81, v81
	v_max_f32_e32 v72, 0xc2700000, v72
	v_max_f32_e32 v73, 0xc2700000, v73
	v_mul_f32_e32 v72, 0xbfb8aa3b, v72
	v_mul_f32_e32 v73, 0xbfb8aa3b, v73
	v_exp_f32_e32 v72, v72
	v_exp_f32_e32 v73, v73
	v_add_f32_e32 v72, 1.0, v72
	v_add_f32_e32 v73, 1.0, v73
	v_rcp_f32_e32 v72, v72
	v_rcp_f32_e32 v73, v73
	s_nop 0
	v_pk_mul_f32 v[80:81], v[72:73], v[80:81]
	v_lshlrev_b32_e32 v72, 16, v75
	v_and_b32_e32 v73, 0xffff0000, v75
	v_max_f32_e32 v74, v72, v72
	v_max_f32_e32 v75, v73, v73
	v_max_f32_e32 v74, 0xc2700000, v74
	v_max_f32_e32 v75, 0xc2700000, v75
	v_mul_f32_e32 v74, 0xbfb8aa3b, v74
	v_mul_f32_e32 v75, 0xbfb8aa3b, v75
	v_exp_f32_e32 v74, v74
	v_exp_f32_e32 v75, v75
	v_add_f32_e32 v74, 1.0, v74
	v_add_f32_e32 v75, 1.0, v75
	v_rcp_f32_e32 v74, v74
	v_rcp_f32_e32 v75, v75
	s_nop 0
	v_pk_mul_f32 v[74:75], v[74:75], v[72:73]
	v_lshlrev_b64 v[72:73], 11, v[118:119]
	v_lshl_add_u64 v[72:73], s[46:47], 0, v[72:73]
	v_lshl_add_u64 v[72:73], v[72:73], 0, s[54:55]
	v_lshl_add_u64 v[94:95], v[72:73], 0, v[0:1]
	v_lshlrev_b32_e32 v72, 16, v71
	v_and_b32_e32 v73, 0xffff0000, v71
	v_pk_add_f32 v[72:73], v[72:73], v[98:99]
	v_lshlrev_b32_e32 v98, 16, v70
	v_and_b32_e32 v99, 0xffff0000, v70
	v_lshlrev_b32_e32 v70, 16, v66
	v_and_b32_e32 v71, 0xffff0000, v66
	v_pk_add_f32 v[66:67], v[98:99], v[70:71]
	v_mov_b32_e32 v98, v73
	v_mov_b32_e32 v99, v67
	v_mov_b32_e32 v70, v72
	v_mov_b32_e32 v71, v66
	v_pk_mul_f32 v[98:99], v[98:99], v[98:99]
	s_nop 0
	v_pk_fma_f32 v[102:103], v[70:71], v[70:71], v[98:99]
	s_waitcnt vmcnt(14)
	v_lshlrev_b32_e32 v70, 16, v62
	v_and_b32_e32 v71, 0xffff0000, v62
	v_max_f32_e32 v62, v70, v70
	v_max_f32_e32 v62, 0xc2700000, v62
	v_mul_f32_e32 v62, 0xbfb8aa3b, v62
	v_exp_f32_e32 v62, v62
	s_nop 0
	v_add_f32_e32 v62, 1.0, v62
	v_rcp_f32_e32 v98, v62
	v_max_f32_e32 v62, v71, v71
	v_max_f32_e32 v62, 0xc2700000, v62
	v_mul_f32_e32 v62, 0xbfb8aa3b, v62
	v_exp_f32_e32 v62, v62
	s_nop 0
	v_add_f32_e32 v62, 1.0, v62
	v_rcp_f32_e32 v99, v62
	s_nop 0
	v_pk_mul_f32 v[70:71], v[98:99], v[70:71]
	v_lshlrev_b32_e32 v98, 16, v69
	v_and_b32_e32 v99, 0xffff0000, v69
	v_pk_add_f32 v[98:99], v[98:99], v[100:101]
	v_lshlrev_b32_e32 v100, 16, v61
	v_and_b32_e32 v101, 0xffff0000, v61
	v_max_f32_e32 v61, v100, v100
	v_max_f32_e32 v61, 0xc2700000, v61
	v_mul_f32_e32 v61, 0xbfb8aa3b, v61
	v_exp_f32_e32 v61, v61
	v_and_b32_e32 v69, 0xffff0000, v64
	v_add_f32_e32 v61, 1.0, v61
	v_rcp_f32_e32 v104, v61
	v_max_f32_e32 v61, v101, v101
	v_max_f32_e32 v61, 0xc2700000, v61
	v_mul_f32_e32 v61, 0xbfb8aa3b, v61
	v_exp_f32_e32 v61, v61
	s_nop 0
	v_add_f32_e32 v61, 1.0, v61
	v_rcp_f32_e32 v105, v61
	s_nop 0
	v_pk_mul_f32 v[100:101], v[104:105], v[100:101]
	v_lshlrev_b32_e32 v104, 16, v68
	v_and_b32_e32 v105, 0xffff0000, v68
	v_lshlrev_b32_e32 v68, 16, v64
	v_pk_add_f32 v[64:65], v[104:105], v[68:69]
	v_mov_b32_e32 v105, v99
	v_mov_b32_e32 v104, v65
	v_mov_b32_e32 v68, v64
	v_mov_b32_e32 v69, v98
	v_pk_mul_f32 v[104:105], v[104:105], v[104:105]
	s_nop 0
	v_pk_fma_f32 v[68:69], v[68:69], v[68:69], v[104:105]
	v_lshlrev_b32_e32 v104, 16, v60
	v_and_b32_e32 v105, 0xffff0000, v60
	v_max_f32_e32 v60, v104, v104
	v_max_f32_e32 v61, v105, v105
	v_max_f32_e32 v60, 0xc2700000, v60
	v_max_f32_e32 v61, 0xc2700000, v61
	v_mul_f32_e32 v60, 0xbfb8aa3b, v60
	v_mul_f32_e32 v61, 0xbfb8aa3b, v61
	v_exp_f32_e32 v60, v60
	v_exp_f32_e32 v61, v61
	v_add_f32_e32 v60, 1.0, v60
	v_add_f32_e32 v61, 1.0, v61
	v_rcp_f32_e32 v60, v60
	v_rcp_f32_e32 v61, v61
	s_nop 0
	v_pk_mul_f32 v[60:61], v[60:61], v[104:105]
	v_mov_b32_e32 v104, v68
	v_mov_b32_e32 v105, v96
	v_mov_b32_e32 v96, v69
	v_pk_add_f32 v[68:69], v[104:105], v[96:97]
	v_mov_b32_e32 v96, v103
	v_mov_b32_e32 v97, v91
	v_pk_add_f32 v[68:69], v[96:97], v[68:69]
	v_mov_b32_e32 v103, v90
	v_pk_add_f32 v[68:69], v[102:103], v[68:69]
	ds_bpermute_b32 v91, v146, v69
	ds_bpermute_b32 v90, v146, v68
	s_waitcnt lgkmcnt(0)
	v_pk_add_f32 v[68:69], v[68:69], v[90:91]
	ds_bpermute_b32 v91, v145, v69
	ds_bpermute_b32 v90, v145, v68
	s_waitcnt lgkmcnt(0)
	v_pk_add_f32 v[68:69], v[68:69], v[90:91]
	ds_bpermute_b32 v91, v3, v69
	ds_bpermute_b32 v90, v3, v68
	s_waitcnt lgkmcnt(0)
	v_pk_add_f32 v[68:69], v[68:69], v[90:91]
	s_nop 0
	v_pk_fma_f32 v[68:69], v[68:69], s[80:81], v[84:85] op_sel_hi:[1,0,0]
	s_nop 0
	v_mul_f32_e32 v62, 0x4b800000, v69
	v_cmp_gt_f32_e64 s[38:39], s79, v69
	v_cmp_gt_f32_e32 vcc, s79, v68
	s_nop 0
	v_cndmask_b32_e64 v62, v69, v62, s[38:39]
	v_rsq_f32_e32 v62, v62
	s_nop 0
	v_mul_f32_e32 v69, 0x45800000, v62
	v_cndmask_b32_e64 v62, v62, v69, s[38:39]
	v_pk_mul_f32 v[76:77], v[76:77], v[62:63] op_sel_hi:[1,0]
	v_pk_mul_f32 v[78:79], v[78:79], v[62:63] op_sel_hi:[1,0]
	v_pk_mul_f32 v[76:77], v[8:9], v[76:77]
	v_pk_mul_f32 v[78:79], v[4:5], v[78:79]
	v_pk_mul_f32 v[76:77], v[80:81], v[76:77]
	v_pk_mul_f32 v[80:81], v[88:89], v[62:63] op_sel_hi:[1,0]
	v_cvt_pk_bf16_f32 v76, v76, v77
	v_pk_mul_f32 v[80:81], v[10:11], v[80:81]
	v_pk_mul_f32 v[78:79], v[82:83], v[78:79]
	v_pk_mul_f32 v[80:81], v[92:93], v[80:81]
	v_cvt_pk_bf16_f32 v78, v78, v79
	v_cvt_pk_bf16_f32 v77, v80, v81
	v_pk_mul_f32 v[80:81], v[86:87], v[62:63] op_sel_hi:[1,0]
	v_mul_f32_e32 v62, 0x4b800000, v68
	v_cndmask_b32_e32 v62, v68, v62, vcc
	v_rsq_f32_e32 v62, v62
	v_pk_mul_f32 v[80:81], v[6:7], v[80:81]
	v_mul_f32_e32 v68, 0x45800000, v62
	v_cndmask_b32_e32 v68, v62, v68, vcc
	v_pk_mul_f32 v[64:65], v[64:65], v[68:69] op_sel_hi:[1,0]
	v_pk_mul_f32 v[74:75], v[74:75], v[80:81]
	v_pk_mul_f32 v[64:65], v[8:9], v[64:65]
	v_cvt_pk_bf16_f32 v79, v74, v75
	v_pk_mul_f32 v[60:61], v[60:61], v[64:65]
	v_pk_mul_f32 v[64:65], v[98:99], v[68:69] op_sel_hi:[1,0]
	v_cvt_pk_bf16_f32 v60, v60, v61
	v_pk_mul_f32 v[64:65], v[10:11], v[64:65]
	v_add_co_u32_e64 v74, s[38:39], s81, v94
	v_pk_mul_f32 v[64:65], v[100:101], v[64:65]
	s_nop 0
	v_addc_co_u32_e64 v75, s[38:39], 0, v95, s[38:39]
	v_cvt_pk_bf16_f32 v61, v64, v65
	v_pk_mul_f32 v[64:65], v[66:67], v[68:69] op_sel_hi:[1,0]
	v_pk_mul_f32 v[68:69], v[72:73], v[68:69] op_sel_hi:[1,0]
	v_pk_mul_f32 v[64:65], v[4:5], v[64:65]
	v_pk_mul_f32 v[68:69], v[6:7], v[68:69]
	v_pk_mul_f32 v[64:65], v[70:71], v[64:65]
	s_waitcnt vmcnt(9)
	v_lshlrev_b32_e32 v72, 16, v43
	v_cvt_pk_bf16_f32 v62, v64, v65
	v_lshlrev_b32_e32 v64, 16, v63
	v_and_b32_e32 v65, 0xffff0000, v63
	v_max_f32_e32 v63, v64, v64
	v_max_f32_e32 v63, 0xc2700000, v63
	v_mul_f32_e32 v63, 0xbfb8aa3b, v63
	v_exp_f32_e32 v63, v63
	v_and_b32_e32 v73, 0xffff0000, v43
	global_store_dwordx4 v[74:75], v[76:79], off offset:1024
	v_lshlrev_b32_e32 v74, 16, v41
	v_add_f32_e32 v63, 1.0, v63
	v_rcp_f32_e32 v66, v63
	v_max_f32_e32 v63, v65, v65
	v_max_f32_e32 v63, 0xc2700000, v63
	v_mul_f32_e32 v63, 0xbfb8aa3b, v63
	v_exp_f32_e32 v63, v63
	v_and_b32_e32 v75, 0xffff0000, v41
	v_add_f32_e32 v63, 1.0, v63
	v_rcp_f32_e32 v67, v63
	s_nop 0
	v_pk_mul_f32 v[64:65], v[66:67], v[64:65]
	s_nop 0
	v_pk_mul_f32 v[64:65], v[64:65], v[68:69]
	v_lshlrev_b32_e32 v66, 16, v57
	v_cvt_pk_bf16_f32 v63, v64, v65
	v_lshlrev_b64 v[64:65], 11, v[116:117]
	v_lshl_add_u64 v[64:65], s[46:47], 0, v[64:65]
	v_lshl_add_u64 v[64:65], v[64:65], 0, s[54:55]
	v_lshl_add_u64 v[64:65], v[64:65], 0, v[0:1]
	v_add_co_u32_e32 v64, vcc, s81, v64
	v_and_b32_e32 v67, 0xffff0000, v57
	s_nop 0
	v_addc_co_u32_e32 v65, vcc, 0, v65, vcc
	global_store_dwordx4 v[64:65], v[60:63], off offset:1024
	s_nop 1
	v_lshlrev_b32_e32 v60, 16, v55
	v_and_b32_e32 v61, 0xffff0000, v55
	v_lshlrev_b32_e32 v62, 16, v59
	v_and_b32_e32 v63, 0xffff0000, v59
	v_pk_add_f32 v[60:61], v[60:61], v[62:63]
	v_lshlrev_b32_e32 v62, 16, v54
	v_and_b32_e32 v63, 0xffff0000, v54
	v_lshlrev_b32_e32 v54, 16, v58
	v_and_b32_e32 v55, 0xffff0000, v58
	v_pk_add_f32 v[54:55], v[62:63], v[54:55]
	v_mov_b32_e32 v62, v61
	v_mov_b32_e32 v63, v55
	v_mov_b32_e32 v58, v60
	v_mov_b32_e32 v59, v54
	v_pk_mul_f32 v[62:63], v[62:63], v[62:63]
	s_nop 0
	v_pk_fma_f32 v[64:65], v[58:59], v[58:59], v[62:63]
	v_lshlrev_b32_e32 v58, 16, v50
	v_and_b32_e32 v59, 0xffff0000, v50
	v_max_f32_e32 v50, v58, v58
	v_max_f32_e32 v50, 0xc2700000, v50
	v_mul_f32_e32 v50, 0xbfb8aa3b, v50
	v_exp_f32_e32 v50, v50
	s_nop 0
	v_add_f32_e32 v50, 1.0, v50
	v_rcp_f32_e32 v62, v50
	v_max_f32_e32 v50, v59, v59
	v_max_f32_e32 v50, 0xc2700000, v50
	v_mul_f32_e32 v50, 0xbfb8aa3b, v50
	v_exp_f32_e32 v50, v50
	s_nop 0
	v_add_f32_e32 v50, 1.0, v50
	v_rcp_f32_e32 v63, v50
	s_nop 0
	v_pk_mul_f32 v[58:59], v[62:63], v[58:59]
	v_lshlrev_b32_e32 v62, 16, v53
	v_and_b32_e32 v63, 0xffff0000, v53
	v_pk_add_f32 v[62:63], v[62:63], v[66:67]
	v_lshlrev_b32_e32 v66, 16, v49
	v_and_b32_e32 v67, 0xffff0000, v49
	v_max_f32_e32 v49, v66, v66
	v_max_f32_e32 v49, 0xc2700000, v49
	v_mul_f32_e32 v49, 0xbfb8aa3b, v49
	v_exp_f32_e32 v49, v49
	v_and_b32_e32 v53, 0xffff0000, v56
	v_mov_b32_e32 v57, v62
	v_add_f32_e32 v49, 1.0, v49
	v_rcp_f32_e32 v68, v49
	v_max_f32_e32 v49, v67, v67
	v_max_f32_e32 v49, 0xc2700000, v49
	v_mul_f32_e32 v49, 0xbfb8aa3b, v49
	v_exp_f32_e32 v49, v49
	s_nop 0
	v_add_f32_e32 v49, 1.0, v49
	v_rcp_f32_e32 v69, v49
	s_nop 0
	v_pk_mul_f32 v[66:67], v[68:69], v[66:67]
	v_lshlrev_b32_e32 v68, 16, v52
	v_and_b32_e32 v69, 0xffff0000, v52
	v_lshlrev_b32_e32 v52, 16, v56
	v_pk_add_f32 v[52:53], v[68:69], v[52:53]
	v_mov_b32_e32 v69, v63
	v_mov_b32_e32 v68, v53
	v_mov_b32_e32 v56, v52
	v_pk_mul_f32 v[68:69], v[68:69], v[68:69]
	s_nop 0
	v_pk_fma_f32 v[70:71], v[56:57], v[56:57], v[68:69]
	v_lshlrev_b32_e32 v56, 16, v48
	v_and_b32_e32 v57, 0xffff0000, v48
	v_max_f32_e32 v48, v56, v56
	v_max_f32_e32 v49, v57, v57
	v_max_f32_e32 v48, 0xc2700000, v48
	v_max_f32_e32 v49, 0xc2700000, v49
	v_mul_f32_e32 v48, 0xbfb8aa3b, v48
	v_mul_f32_e32 v49, 0xbfb8aa3b, v49
	v_exp_f32_e32 v48, v48
	v_exp_f32_e32 v49, v49
	v_add_f32_e32 v48, 1.0, v48
	v_add_f32_e32 v49, 1.0, v49
	v_rcp_f32_e32 v48, v48
	v_rcp_f32_e32 v49, v49
	s_nop 0
	v_pk_mul_f32 v[56:57], v[48:49], v[56:57]
	v_lshlrev_b32_e32 v48, 16, v51
	v_and_b32_e32 v49, 0xffff0000, v51
	v_max_f32_e32 v50, v48, v48
	v_max_f32_e32 v51, v49, v49
	v_max_f32_e32 v50, 0xc2700000, v50
	v_max_f32_e32 v51, 0xc2700000, v51
	v_mul_f32_e32 v50, 0xbfb8aa3b, v50
	v_mul_f32_e32 v51, 0xbfb8aa3b, v51
	v_exp_f32_e32 v50, v50
	v_exp_f32_e32 v51, v51
	v_add_f32_e32 v50, 1.0, v50
	v_add_f32_e32 v51, 1.0, v51
	v_rcp_f32_e32 v50, v50
	v_rcp_f32_e32 v51, v51
	s_nop 0
	v_pk_mul_f32 v[50:51], v[50:51], v[48:49]
	v_lshlrev_b64 v[48:49], 11, v[114:115]
	v_lshl_add_u64 v[48:49], s[46:47], 0, v[48:49]
	v_lshl_add_u64 v[48:49], v[48:49], 0, s[54:55]
	v_lshl_add_u64 v[68:69], v[48:49], 0, v[0:1]
	v_lshlrev_b32_e32 v48, 16, v47
	v_and_b32_e32 v49, 0xffff0000, v47
	v_pk_add_f32 v[48:49], v[48:49], v[72:73]
	v_lshlrev_b32_e32 v72, 16, v46
	v_and_b32_e32 v73, 0xffff0000, v46
	v_lshlrev_b32_e32 v46, 16, v42
	v_and_b32_e32 v47, 0xffff0000, v42
	v_pk_add_f32 v[42:43], v[72:73], v[46:47]
	v_mov_b32_e32 v72, v49
	v_mov_b32_e32 v73, v43
	v_mov_b32_e32 v46, v48
	v_mov_b32_e32 v47, v42
	v_pk_mul_f32 v[72:73], v[72:73], v[72:73]
	s_nop 0
	v_pk_fma_f32 v[76:77], v[46:47], v[46:47], v[72:73]
	s_waitcnt vmcnt(10)
	v_lshlrev_b32_e32 v46, 16, v38
	v_and_b32_e32 v47, 0xffff0000, v38
	v_max_f32_e32 v38, v46, v46
	v_max_f32_e32 v38, 0xc2700000, v38
	v_mul_f32_e32 v38, 0xbfb8aa3b, v38
	v_exp_f32_e32 v38, v38
	s_nop 0
	v_add_f32_e32 v38, 1.0, v38
	v_rcp_f32_e32 v72, v38
	v_max_f32_e32 v38, v47, v47
	v_max_f32_e32 v38, 0xc2700000, v38
	v_mul_f32_e32 v38, 0xbfb8aa3b, v38
	v_exp_f32_e32 v38, v38
	s_nop 0
	v_add_f32_e32 v38, 1.0, v38
	v_rcp_f32_e32 v73, v38
	s_nop 0
	v_pk_mul_f32 v[46:47], v[72:73], v[46:47]
	v_lshlrev_b32_e32 v72, 16, v45
	v_and_b32_e32 v73, 0xffff0000, v45
	v_pk_add_f32 v[72:73], v[72:73], v[74:75]
	v_lshlrev_b32_e32 v74, 16, v37
	v_and_b32_e32 v75, 0xffff0000, v37
	v_max_f32_e32 v37, v74, v74
	v_max_f32_e32 v37, 0xc2700000, v37
	v_mul_f32_e32 v37, 0xbfb8aa3b, v37
	v_exp_f32_e32 v37, v37
	v_and_b32_e32 v45, 0xffff0000, v40
	v_add_f32_e32 v37, 1.0, v37
	v_rcp_f32_e32 v78, v37
	v_max_f32_e32 v37, v75, v75
	v_max_f32_e32 v37, 0xc2700000, v37
	v_mul_f32_e32 v37, 0xbfb8aa3b, v37
	v_exp_f32_e32 v37, v37
	s_nop 0
	v_add_f32_e32 v37, 1.0, v37
	v_rcp_f32_e32 v79, v37
	s_nop 0
	v_pk_mul_f32 v[74:75], v[78:79], v[74:75]
	v_lshlrev_b32_e32 v78, 16, v44
	v_and_b32_e32 v79, 0xffff0000, v44
	v_lshlrev_b32_e32 v44, 16, v40
	v_pk_add_f32 v[40:41], v[78:79], v[44:45]
	v_mov_b32_e32 v79, v73
	v_mov_b32_e32 v78, v41
	v_mov_b32_e32 v44, v40
	v_mov_b32_e32 v45, v72
	v_pk_mul_f32 v[78:79], v[78:79], v[78:79]
	s_nop 0
	v_pk_fma_f32 v[44:45], v[44:45], v[44:45], v[78:79]
	v_lshlrev_b32_e32 v78, 16, v36
	v_and_b32_e32 v79, 0xffff0000, v36
	v_max_f32_e32 v36, v78, v78
	v_max_f32_e32 v37, v79, v79
	v_max_f32_e32 v36, 0xc2700000, v36
	v_max_f32_e32 v37, 0xc2700000, v37
	v_mul_f32_e32 v36, 0xbfb8aa3b, v36
	v_mul_f32_e32 v37, 0xbfb8aa3b, v37
	v_exp_f32_e32 v36, v36
	v_exp_f32_e32 v37, v37
	v_add_f32_e32 v36, 1.0, v36
	v_add_f32_e32 v37, 1.0, v37
	v_rcp_f32_e32 v36, v36
	v_rcp_f32_e32 v37, v37
	s_nop 0
	v_pk_mul_f32 v[36:37], v[36:37], v[78:79]
	v_mov_b32_e32 v78, v44
	v_mov_b32_e32 v79, v70
	v_mov_b32_e32 v70, v45
	v_pk_add_f32 v[44:45], v[78:79], v[70:71]
	v_mov_b32_e32 v70, v77
	v_mov_b32_e32 v71, v65
	v_pk_add_f32 v[44:45], v[70:71], v[44:45]
	v_mov_b32_e32 v77, v64
	v_pk_add_f32 v[44:45], v[76:77], v[44:45]
	ds_bpermute_b32 v65, v146, v45
	ds_bpermute_b32 v64, v146, v44
	s_waitcnt lgkmcnt(0)
	v_pk_add_f32 v[44:45], v[44:45], v[64:65]
	ds_bpermute_b32 v65, v145, v45
	ds_bpermute_b32 v64, v145, v44
	s_waitcnt lgkmcnt(0)
	v_pk_add_f32 v[44:45], v[44:45], v[64:65]
	ds_bpermute_b32 v65, v3, v45
	ds_bpermute_b32 v64, v3, v44
	s_waitcnt lgkmcnt(0)
	v_pk_add_f32 v[44:45], v[44:45], v[64:65]
	s_nop 0
	v_pk_fma_f32 v[44:45], v[44:45], s[80:81], v[84:85] op_sel_hi:[1,0,0]
	s_nop 0
	v_mul_f32_e32 v38, 0x4b800000, v45
	v_cmp_gt_f32_e64 s[38:39], s79, v45
	v_cmp_gt_f32_e32 vcc, s79, v44
	s_nop 0
	v_cndmask_b32_e64 v38, v45, v38, s[38:39]
	v_rsq_f32_e32 v38, v38
	s_nop 0
	v_mul_f32_e32 v45, 0x45800000, v38
	v_cndmask_b32_e64 v38, v38, v45, s[38:39]
	v_pk_mul_f32 v[52:53], v[52:53], v[38:39] op_sel_hi:[1,0]
	v_pk_mul_f32 v[54:55], v[54:55], v[38:39] op_sel_hi:[1,0]
	v_pk_mul_f32 v[52:53], v[8:9], v[52:53]
	v_pk_mul_f32 v[54:55], v[4:5], v[54:55]
	v_pk_mul_f32 v[52:53], v[56:57], v[52:53]
	v_pk_mul_f32 v[56:57], v[62:63], v[38:39] op_sel_hi:[1,0]
	v_cvt_pk_bf16_f32 v52, v52, v53
	v_pk_mul_f32 v[56:57], v[10:11], v[56:57]
	v_pk_mul_f32 v[54:55], v[58:59], v[54:55]
	v_pk_mul_f32 v[56:57], v[66:67], v[56:57]
	v_cvt_pk_bf16_f32 v54, v54, v55
	v_cvt_pk_bf16_f32 v53, v56, v57
	v_pk_mul_f32 v[56:57], v[60:61], v[38:39] op_sel_hi:[1,0]
	v_mul_f32_e32 v38, 0x4b800000, v44
	v_cndmask_b32_e32 v38, v44, v38, vcc
	v_rsq_f32_e32 v38, v38
	v_pk_mul_f32 v[56:57], v[6:7], v[56:57]
	v_mul_f32_e32 v44, 0x45800000, v38
	v_cndmask_b32_e32 v44, v38, v44, vcc
	v_pk_mul_f32 v[40:41], v[40:41], v[44:45] op_sel_hi:[1,0]
	v_pk_mul_f32 v[50:51], v[50:51], v[56:57]
	v_pk_mul_f32 v[40:41], v[8:9], v[40:41]
	v_cvt_pk_bf16_f32 v55, v50, v51
	v_pk_mul_f32 v[36:37], v[36:37], v[40:41]
	v_pk_mul_f32 v[40:41], v[72:73], v[44:45] op_sel_hi:[1,0]
	v_cvt_pk_bf16_f32 v36, v36, v37
	v_pk_mul_f32 v[40:41], v[10:11], v[40:41]
	v_add_co_u32_e64 v50, s[38:39], s81, v68
	v_pk_mul_f32 v[40:41], v[74:75], v[40:41]
	s_nop 0
	v_addc_co_u32_e64 v51, s[38:39], 0, v69, s[38:39]
	v_cvt_pk_bf16_f32 v37, v40, v41
	v_pk_mul_f32 v[40:41], v[42:43], v[44:45] op_sel_hi:[1,0]
	v_pk_mul_f32 v[44:45], v[48:49], v[44:45] op_sel_hi:[1,0]
	v_pk_mul_f32 v[40:41], v[4:5], v[40:41]
	v_pk_mul_f32 v[44:45], v[6:7], v[44:45]
	v_pk_mul_f32 v[40:41], v[46:47], v[40:41]
	s_waitcnt vmcnt(5)
	v_lshlrev_b32_e32 v48, 16, v23
	v_cvt_pk_bf16_f32 v38, v40, v41
	v_lshlrev_b32_e32 v40, 16, v39
	v_and_b32_e32 v41, 0xffff0000, v39
	v_max_f32_e32 v39, v40, v40
	v_max_f32_e32 v39, 0xc2700000, v39
	v_mul_f32_e32 v39, 0xbfb8aa3b, v39
	v_exp_f32_e32 v39, v39
	v_and_b32_e32 v49, 0xffff0000, v23
	global_store_dwordx4 v[50:51], v[52:55], off offset:1024
	v_lshlrev_b32_e32 v50, 16, v21
	v_add_f32_e32 v39, 1.0, v39
	v_rcp_f32_e32 v42, v39
	v_max_f32_e32 v39, v41, v41
	v_max_f32_e32 v39, 0xc2700000, v39
	v_mul_f32_e32 v39, 0xbfb8aa3b, v39
	v_exp_f32_e32 v39, v39
	v_and_b32_e32 v51, 0xffff0000, v21
	v_add_f32_e32 v39, 1.0, v39
	v_rcp_f32_e32 v43, v39
	s_nop 0
	v_pk_mul_f32 v[40:41], v[42:43], v[40:41]
	s_nop 0
	v_pk_mul_f32 v[40:41], v[40:41], v[44:45]
	v_lshlrev_b32_e32 v42, 16, v33
	v_cvt_pk_bf16_f32 v39, v40, v41
	v_lshlrev_b64 v[40:41], 11, v[112:113]
	v_lshl_add_u64 v[40:41], s[46:47], 0, v[40:41]
	v_lshl_add_u64 v[40:41], v[40:41], 0, s[54:55]
	v_lshl_add_u64 v[40:41], v[40:41], 0, v[0:1]
	v_add_co_u32_e32 v40, vcc, s81, v40
	v_and_b32_e32 v43, 0xffff0000, v33
	s_nop 0
	v_addc_co_u32_e32 v41, vcc, 0, v41, vcc
	global_store_dwordx4 v[40:41], v[36:39], off offset:1024
	s_nop 1
	v_lshlrev_b32_e32 v36, 16, v31
	v_and_b32_e32 v37, 0xffff0000, v31
	v_lshlrev_b32_e32 v38, 16, v35
	v_and_b32_e32 v39, 0xffff0000, v35
	v_pk_add_f32 v[36:37], v[36:37], v[38:39]
	v_lshlrev_b32_e32 v38, 16, v30
	v_and_b32_e32 v39, 0xffff0000, v30
	v_lshlrev_b32_e32 v30, 16, v34
	v_and_b32_e32 v31, 0xffff0000, v34
	v_pk_add_f32 v[30:31], v[38:39], v[30:31]
	v_mov_b32_e32 v38, v37
	v_mov_b32_e32 v39, v31
	v_mov_b32_e32 v34, v36
	v_mov_b32_e32 v35, v30
	v_pk_mul_f32 v[38:39], v[38:39], v[38:39]
	s_nop 0
	v_pk_fma_f32 v[40:41], v[34:35], v[34:35], v[38:39]
	v_lshlrev_b32_e32 v34, 16, v26
	v_and_b32_e32 v35, 0xffff0000, v26
	v_max_f32_e32 v26, v34, v34
	v_max_f32_e32 v26, 0xc2700000, v26
	v_mul_f32_e32 v26, 0xbfb8aa3b, v26
	v_exp_f32_e32 v26, v26
	s_nop 0
	v_add_f32_e32 v26, 1.0, v26
	v_rcp_f32_e32 v38, v26
	v_max_f32_e32 v26, v35, v35
	v_max_f32_e32 v26, 0xc2700000, v26
	v_mul_f32_e32 v26, 0xbfb8aa3b, v26
	v_exp_f32_e32 v26, v26
	s_nop 0
	v_add_f32_e32 v26, 1.0, v26
	v_rcp_f32_e32 v39, v26
	s_nop 0
	v_pk_mul_f32 v[34:35], v[38:39], v[34:35]
	v_lshlrev_b32_e32 v38, 16, v29
	v_and_b32_e32 v39, 0xffff0000, v29
	v_pk_add_f32 v[38:39], v[38:39], v[42:43]
	v_lshlrev_b32_e32 v42, 16, v25
	v_and_b32_e32 v43, 0xffff0000, v25
	v_max_f32_e32 v25, v42, v42
	v_max_f32_e32 v25, 0xc2700000, v25
	v_mul_f32_e32 v25, 0xbfb8aa3b, v25
	v_exp_f32_e32 v25, v25
	v_and_b32_e32 v29, 0xffff0000, v32
	v_mov_b32_e32 v33, v38
	v_add_f32_e32 v25, 1.0, v25
	v_rcp_f32_e32 v44, v25
	v_max_f32_e32 v25, v43, v43
	v_max_f32_e32 v25, 0xc2700000, v25
	v_mul_f32_e32 v25, 0xbfb8aa3b, v25
	v_exp_f32_e32 v25, v25
	s_nop 0
	v_add_f32_e32 v25, 1.0, v25
	v_rcp_f32_e32 v45, v25
	s_nop 0
	v_pk_mul_f32 v[42:43], v[44:45], v[42:43]
	v_lshlrev_b32_e32 v44, 16, v28
	v_and_b32_e32 v45, 0xffff0000, v28
	v_lshlrev_b32_e32 v28, 16, v32
	v_pk_add_f32 v[28:29], v[44:45], v[28:29]
	v_mov_b32_e32 v45, v39
	v_mov_b32_e32 v44, v29
	v_mov_b32_e32 v32, v28
	v_pk_mul_f32 v[44:45], v[44:45], v[44:45]
	s_nop 0
	v_pk_fma_f32 v[46:47], v[32:33], v[32:33], v[44:45]
	v_lshlrev_b32_e32 v32, 16, v24
	v_and_b32_e32 v33, 0xffff0000, v24
	v_max_f32_e32 v24, v32, v32
	v_max_f32_e32 v25, v33, v33
	v_max_f32_e32 v24, 0xc2700000, v24
	v_max_f32_e32 v25, 0xc2700000, v25
	v_mul_f32_e32 v24, 0xbfb8aa3b, v24
	v_mul_f32_e32 v25, 0xbfb8aa3b, v25
	v_exp_f32_e32 v24, v24
	v_exp_f32_e32 v25, v25
	v_add_f32_e32 v24, 1.0, v24
	v_add_f32_e32 v25, 1.0, v25
	v_rcp_f32_e32 v24, v24
	v_rcp_f32_e32 v25, v25
	s_nop 0
	v_pk_mul_f32 v[32:33], v[24:25], v[32:33]
	v_lshlrev_b32_e32 v24, 16, v27
	v_and_b32_e32 v25, 0xffff0000, v27
	v_max_f32_e32 v26, v24, v24
	v_max_f32_e32 v27, v25, v25
	v_max_f32_e32 v26, 0xc2700000, v26
	v_max_f32_e32 v27, 0xc2700000, v27
	v_mul_f32_e32 v26, 0xbfb8aa3b, v26
	v_mul_f32_e32 v27, 0xbfb8aa3b, v27
	v_exp_f32_e32 v26, v26
	v_exp_f32_e32 v27, v27
	v_add_f32_e32 v26, 1.0, v26
	v_add_f32_e32 v27, 1.0, v27
	v_rcp_f32_e32 v26, v26
	v_rcp_f32_e32 v27, v27
	s_nop 0
	v_pk_mul_f32 v[26:27], v[26:27], v[24:25]
	v_lshlrev_b64 v[24:25], 11, v[110:111]
	v_lshl_add_u64 v[24:25], s[46:47], 0, v[24:25]
	v_lshl_add_u64 v[24:25], v[24:25], 0, s[54:55]
	v_lshl_add_u64 v[44:45], v[24:25], 0, v[0:1]
	v_lshlrev_b32_e32 v24, 16, v19
	v_and_b32_e32 v25, 0xffff0000, v19
	v_pk_add_f32 v[24:25], v[24:25], v[48:49]
	v_lshlrev_b32_e32 v48, 16, v18
	v_and_b32_e32 v49, 0xffff0000, v18
	v_lshlrev_b32_e32 v18, 16, v22
	v_and_b32_e32 v19, 0xffff0000, v22
	v_pk_add_f32 v[18:19], v[48:49], v[18:19]
	v_mov_b32_e32 v48, v25
	v_mov_b32_e32 v49, v19
	v_mov_b32_e32 v22, v24
	v_mov_b32_e32 v23, v18
	v_pk_mul_f32 v[48:49], v[48:49], v[48:49]
	s_nop 0
	v_pk_fma_f32 v[52:53], v[22:23], v[22:23], v[48:49]
	s_waitcnt vmcnt(6)
	v_lshlrev_b32_e32 v22, 16, v14
	v_and_b32_e32 v23, 0xffff0000, v14
	v_max_f32_e32 v14, v22, v22
	v_max_f32_e32 v14, 0xc2700000, v14
	v_mul_f32_e32 v14, 0xbfb8aa3b, v14
	v_exp_f32_e32 v14, v14
	s_nop 0
	v_add_f32_e32 v14, 1.0, v14
	v_rcp_f32_e32 v48, v14
	v_max_f32_e32 v14, v23, v23
	v_max_f32_e32 v14, 0xc2700000, v14
	v_mul_f32_e32 v14, 0xbfb8aa3b, v14
	v_exp_f32_e32 v14, v14
	s_nop 0
	v_add_f32_e32 v14, 1.0, v14
	v_rcp_f32_e32 v49, v14
	s_nop 0
	v_pk_mul_f32 v[22:23], v[48:49], v[22:23]
	v_lshlrev_b32_e32 v48, 16, v17
	v_and_b32_e32 v49, 0xffff0000, v17
	v_pk_add_f32 v[48:49], v[48:49], v[50:51]
	v_lshlrev_b32_e32 v50, 16, v13
	v_and_b32_e32 v51, 0xffff0000, v13
	v_max_f32_e32 v13, v50, v50
	v_max_f32_e32 v13, 0xc2700000, v13
	v_mul_f32_e32 v13, 0xbfb8aa3b, v13
	v_exp_f32_e32 v13, v13
	v_and_b32_e32 v17, 0xffff0000, v20
	v_mov_b32_e32 v21, v48
	v_add_f32_e32 v13, 1.0, v13
	v_rcp_f32_e32 v54, v13
	v_max_f32_e32 v13, v51, v51
	v_max_f32_e32 v13, 0xc2700000, v13
	v_mul_f32_e32 v13, 0xbfb8aa3b, v13
	v_exp_f32_e32 v13, v13
	s_nop 0
	v_add_f32_e32 v13, 1.0, v13
	v_rcp_f32_e32 v55, v13
	s_nop 0
	v_pk_mul_f32 v[50:51], v[54:55], v[50:51]
	v_lshlrev_b32_e32 v54, 16, v16
	v_and_b32_e32 v55, 0xffff0000, v16
	v_lshlrev_b32_e32 v16, 16, v20
	v_pk_add_f32 v[16:17], v[54:55], v[16:17]
	v_mov_b32_e32 v55, v49
	v_mov_b32_e32 v54, v17
	v_mov_b32_e32 v20, v16
	v_pk_mul_f32 v[54:55], v[54:55], v[54:55]
	s_nop 0
	v_pk_fma_f32 v[20:21], v[20:21], v[20:21], v[54:55]
	v_lshlrev_b32_e32 v54, 16, v12
	v_and_b32_e32 v55, 0xffff0000, v12
	v_max_f32_e32 v12, v54, v54
	v_max_f32_e32 v13, v55, v55
	v_max_f32_e32 v12, 0xc2700000, v12
	v_max_f32_e32 v13, 0xc2700000, v13
	v_mul_f32_e32 v12, 0xbfb8aa3b, v12
	v_mul_f32_e32 v13, 0xbfb8aa3b, v13
	v_exp_f32_e32 v12, v12
	v_exp_f32_e32 v13, v13
	v_add_f32_e32 v12, 1.0, v12
	v_add_f32_e32 v13, 1.0, v13
	v_rcp_f32_e32 v12, v12
	v_rcp_f32_e32 v13, v13
	s_nop 0
	v_pk_mul_f32 v[12:13], v[12:13], v[54:55]
	v_mov_b32_e32 v54, v20
	v_mov_b32_e32 v55, v46
	v_mov_b32_e32 v46, v21
	v_pk_add_f32 v[20:21], v[54:55], v[46:47]
	v_mov_b32_e32 v46, v53
	v_mov_b32_e32 v47, v41
	v_pk_add_f32 v[20:21], v[46:47], v[20:21]
	v_mov_b32_e32 v53, v40
	v_pk_add_f32 v[20:21], v[52:53], v[20:21]
	ds_bpermute_b32 v41, v146, v21
	ds_bpermute_b32 v40, v146, v20
	s_waitcnt lgkmcnt(0)
	v_pk_add_f32 v[20:21], v[20:21], v[40:41]
	ds_bpermute_b32 v41, v145, v21
	ds_bpermute_b32 v40, v145, v20
	s_waitcnt lgkmcnt(0)
	v_pk_add_f32 v[20:21], v[20:21], v[40:41]
	ds_bpermute_b32 v41, v3, v21
	ds_bpermute_b32 v40, v3, v20
	s_waitcnt lgkmcnt(0)
	v_pk_add_f32 v[20:21], v[20:21], v[40:41]
	s_nop 0
	v_pk_fma_f32 v[20:21], v[20:21], s[80:81], v[84:85] op_sel_hi:[1,0,0]
	s_nop 0
	v_mul_f32_e32 v3, 0x4b800000, v21
	v_cmp_gt_f32_e64 s[38:39], s79, v21
	v_cmp_gt_f32_e32 vcc, s79, v20
	s_nop 0
	v_cndmask_b32_e64 v3, v21, v3, s[38:39]
	v_rsq_f32_e32 v3, v3
	s_nop 0
	v_mul_f32_e32 v14, 0x45800000, v3
	v_cndmask_b32_e64 v14, v3, v14, s[38:39]
	v_mul_f32_e32 v3, 0x4b800000, v20
	v_pk_mul_f32 v[28:29], v[28:29], v[14:15] op_sel_hi:[1,0]
	v_cndmask_b32_e32 v3, v20, v3, vcc
	v_pk_mul_f32 v[28:29], v[8:9], v[28:29]
	v_rsq_f32_e32 v3, v3
	v_pk_mul_f32 v[28:29], v[32:33], v[28:29]
	v_pk_mul_f32 v[32:33], v[38:39], v[14:15] op_sel_hi:[1,0]
	v_cvt_pk_bf16_f32 v28, v28, v29
	v_pk_mul_f32 v[32:33], v[10:11], v[32:33]
	v_pk_mul_f32 v[30:31], v[30:31], v[14:15] op_sel_hi:[1,0]
	v_pk_mul_f32 v[32:33], v[42:43], v[32:33]
	v_pk_mul_f32 v[30:31], v[4:5], v[30:31]
	v_cvt_pk_bf16_f32 v29, v32, v33
	v_pk_mul_f32 v[32:33], v[36:37], v[14:15] op_sel_hi:[1,0]
	v_mul_f32_e32 v14, 0x45800000, v3
	v_cndmask_b32_e32 v14, v3, v14, vcc
	v_pk_mul_f32 v[16:17], v[16:17], v[14:15] op_sel_hi:[1,0]
	v_pk_mul_f32 v[32:33], v[6:7], v[32:33]
	v_pk_mul_f32 v[8:9], v[8:9], v[16:17]
	v_pk_mul_f32 v[30:31], v[34:35], v[30:31]
	v_pk_mul_f32 v[8:9], v[12:13], v[8:9]
	v_pk_mul_f32 v[12:13], v[48:49], v[14:15] op_sel_hi:[1,0]
	v_cvt_pk_bf16_f32 v8, v8, v9
	v_pk_mul_f32 v[10:11], v[10:11], v[12:13]
	v_pk_mul_f32 v[26:27], v[26:27], v[32:33]
	v_pk_mul_f32 v[10:11], v[50:51], v[10:11]
	v_cvt_pk_bf16_f32 v30, v30, v31
	v_cvt_pk_bf16_f32 v9, v10, v11
	v_pk_mul_f32 v[10:11], v[18:19], v[14:15] op_sel_hi:[1,0]
	v_cvt_pk_bf16_f32 v31, v26, v27
	v_pk_mul_f32 v[4:5], v[4:5], v[10:11]
	v_add_co_u32_e64 v26, s[38:39], s81, v44
	v_pk_mul_f32 v[4:5], v[22:23], v[4:5]
	s_nop 0
	v_addc_co_u32_e64 v27, s[38:39], 0, v45, s[38:39]
	v_cvt_pk_bf16_f32 v10, v4, v5
	v_lshlrev_b32_e32 v4, 16, v15
	v_max_f32_e32 v3, v4, v4
	v_max_f32_e32 v3, 0xc2700000, v3
	v_mul_f32_e32 v3, 0xbfb8aa3b, v3
	v_exp_f32_e32 v3, v3
	v_and_b32_e32 v5, 0xffff0000, v15
	v_pk_mul_f32 v[14:15], v[24:25], v[14:15] op_sel_hi:[1,0]
	global_store_dwordx4 v[26:27], v[28:31], off offset:1024
	v_add_f32_e32 v3, 1.0, v3
	v_rcp_f32_e32 v12, v3
	v_max_f32_e32 v3, v5, v5
	v_max_f32_e32 v3, 0xc2700000, v3
	v_mul_f32_e32 v3, 0xbfb8aa3b, v3
	v_exp_f32_e32 v3, v3
	v_pk_mul_f32 v[6:7], v[6:7], v[14:15]
	v_add_f32_e32 v3, 1.0, v3
	v_rcp_f32_e32 v13, v3
	s_nop 0
	v_pk_mul_f32 v[4:5], v[12:13], v[4:5]
	s_nop 0
	v_pk_mul_f32 v[4:5], v[4:5], v[6:7]
	s_nop 0
	v_cvt_pk_bf16_f32 v11, v4, v5
	v_lshlrev_b64 v[4:5], 11, v[108:109]
	v_lshl_add_u64 v[4:5], s[46:47], 0, v[4:5]
	v_lshl_add_u64 v[4:5], v[4:5], 0, s[54:55]
	v_lshl_add_u64 v[0:1], v[4:5], 0, v[0:1]
	v_add_co_u32_e32 v0, vcc, 0x11000000, v0
	s_nop 1
	v_addc_co_u32_e32 v1, vcc, 0, v1, vcc
	global_store_dwordx4 v[0:1], v[8:11], off offset:1024
	s_barrier
	s_cbranch_scc0 .LBB0_684
